# GEMM epilogues: write-through stores kept only on a workgroup's last unit of the phase; earlier units use write-back stores so the next K-loop's counted waits do not drain memory acks
# speedup vs baseline: 1.0084x; 1.0041x over previous
; __device__ __forceinline__ unsigned pk2(float lo, float hi) { unsigned r; asm volatile("v_cvt_pk_bf16_f32 %0, %1, %2" : "=v"(r) : "v"(lo), "v"(hi)); return r; }
; template <int CTRL> __device__ __forceinline__ float dppz(float x) { return __builtin_bit_cast(float, __builtin_amdgcn_update_dpp(0, __builtin_bit_cast(int, x), CTRL, 0xf, 0xf, true)); }
;     __device__ __forceinline__ void fast(const f32x4 (&acc)[2][2][4][2], const pg8::Unit& u, int wr, int wc, int fr, int fq, RsCache& rsc) const {
;     ...
;             for (int m = 0; m < 4; ++m) {
;                 const int row = rowb + m * 16 + fr; const float s = rsc.tab[ai * 64 + m * 16 + fr]; const f32x2 s2 = (f32x2){s, s};
;                 f32x2 g[4], o[4], v[4];
; #pragma unroll
;                 for (int cp = 0; cp < 4; ++cp) { const int n = cp >> 1, e0 = (cp & 1) * 2;
;                     g[cp] = (f32x2){acc[ai][0][m][n][e0], acc[ai][0][m][n][e0 + 1]} * s2; v[cp] = (f32x2){acc[ai][1][m][n][e0], acc[ai][1][m][n][e0 + 1]} * s2; }
; #pragma unroll
;                 for (int cp = 0; cp < 4; ++cp) {
;                     f32x2 p1 = (f32x2){dppz<0x111>(g[cp].x), dppz<0x111>(g[cp].y)}, p2 = (f32x2){dppz<0x112>(g[cp].x), dppz<0x112>(g[cp].y)};
;                     if (m > 0) { p1 += (f32x2){dppz<0x10F>(gp[cp].x), dppz<0x10F>(gp[cp].y)}; p2 += (f32x2){dppz<0x10E>(gp[cp].x), dppz<0x10E>(gp[cp].y)}; }
;                     const f32x2 gv = bb[cp] + w0[cp] * p2 + w1[cp] * p1 + w2[cp] * g[cp];
;                     const f32x2 ea = gv * (-1.44269504089f);
;                     f32x2 ex; ex.x = __builtin_amdgcn_exp2f(ea.x); ex.y = __builtin_amdgcn_exp2f(ea.y);
;                     const f32x2 dn = ex + 1.0f;
;                     f32x2 rc; rc.x = __builtin_amdgcn_rcpf(dn.x); rc.y = __builtin_amdgcn_rcpf(dn.y);
;                     o[cp] = (gv * rc) * v[cp];
;                 }
;                 if (m > 0 || fr >= 2) { uint4 w; w.x = pk2(o[0].x, o[0].y); w.y = pk2(o[1].x, o[1].y); w.z = pk2(o[2].x, o[2].y); w.w = pk2(o[3].x, o[3].y); *(uint4*)(act + (size_t)row * FH + ch) = w; }
.LBB0_276:
	s_or_b64 exec, exec, s[82:83]
	ds_read_b32 v80, v223 offset:320
	s_mov_b32 s2, 0xbfb8aa3b
	v_readlane_b32 s0, v253, 16
	s_waitcnt lgkmcnt(0)
	v_pk_mul_f32 v[64:65], v[54:55], v[80:81] op_sel_hi:[1,0]
	v_pk_mul_f32 v[82:83], v[46:47], v[80:81] op_sel_hi:[1,0]
	v_pk_mul_f32 v[46:47], v[52:53], v[80:81] op_sel_hi:[1,0]
	v_mov_b32_dpp v52, v64 row_shr:2 row_mask:0xf bank_mask:0xf bound_ctrl:1
	v_mov_b32_dpp v53, v65 row_shr:2 row_mask:0xf bank_mask:0xf bound_ctrl:1
	v_pk_mul_f32 v[54:55], v[56:57], v[80:81] op_sel_hi:[1,0]
	v_pk_mul_f32 v[56:57], v[48:49], v[80:81] op_sel_hi:[1,0]
	v_pk_mul_f32 v[48:49], v[50:51], v[80:81] op_sel_hi:[1,0]
	v_pk_mul_f32 v[42:43], v[42:43], v[80:81] op_sel_hi:[1,0]
	v_pk_mul_f32 v[44:45], v[44:45], v[80:81] op_sel_hi:[1,0]
	v_mov_b32_dpp v50, v64 row_shr:1 row_mask:0xf bank_mask:0xf bound_ctrl:1
	v_mov_b32_dpp v51, v65 row_shr:1 row_mask:0xf bank_mask:0xf bound_ctrl:1
	v_mov_b32_dpp v52, v106 row_shl:14 row_mask:0xf bank_mask:0xf
	v_mov_b32_dpp v53, v107 row_shl:14 row_mask:0xf bank_mask:0xf
	v_mov_b32_dpp v50, v106 row_shl:15 row_mask:0xf bank_mask:0xf
	v_mov_b32_dpp v51, v107 row_shl:15 row_mask:0xf bank_mask:0xf
	v_pk_fma_f32 v[52:53], v[90:91], v[52:53], v[102:103]
	v_mov_b32_dpp v80, v54 row_shr:2 row_mask:0xf bank_mask:0xf bound_ctrl:1
	v_pk_fma_f32 v[50:51], v[94:95], v[50:51], v[52:53]
	v_mov_b32_dpp v81, v55 row_shr:2 row_mask:0xf bank_mask:0xf bound_ctrl:1
	v_pk_fma_f32 v[50:51], v[98:99], v[64:65], v[50:51]
	v_pk_mul_f32 v[52:53], v[50:51], s[2:3] op_sel_hi:[1,0]
	v_exp_f32_e32 v52, v52
	v_exp_f32_e32 v53, v53
	v_mov_b32_dpp v80, v86 row_shl:14 row_mask:0xf bank_mask:0xf
	v_mov_b32_dpp v81, v87 row_shl:14 row_mask:0xf bank_mask:0xf
	v_readlane_b32 s1, v253, 17
	v_pk_fma_f32 v[80:81], v[92:93], v[80:81], v[104:105]
	v_pk_add_f32 v[52:53], v[52:53], 1.0 op_sel_hi:[1,0]
	s_nop 0
	v_rcp_f32_e32 v52, v52
	v_rcp_f32_e32 v53, v53
	s_nop 0
	v_pk_mul_f32 v[50:51], v[50:51], v[52:53]
	s_nop 0
	v_pk_mul_f32 v[50:51], v[82:83], v[50:51]
	v_mov_b32_dpp v52, v54 row_shr:1 row_mask:0xf bank_mask:0xf bound_ctrl:1
	v_mov_b32_dpp v53, v55 row_shr:1 row_mask:0xf bank_mask:0xf bound_ctrl:1
	v_mov_b32_dpp v52, v86 row_shl:15 row_mask:0xf bank_mask:0xf
	v_mov_b32_dpp v53, v87 row_shl:15 row_mask:0xf bank_mask:0xf
	v_mov_b32_dpp v82, v78 row_shl:15 row_mask:0xf bank_mask:0xf bound_ctrl:1
	v_pk_fma_f32 v[52:53], v[96:97], v[52:53], v[80:81]
	v_mov_b32_dpp v83, v79 row_shl:15 row_mask:0xf bank_mask:0xf bound_ctrl:1
	v_pk_fma_f32 v[52:53], v[100:101], v[54:55], v[52:53]
	v_mov_b32_dpp v78, v78 row_shl:14 row_mask:0xf bank_mask:0xf bound_ctrl:1
	v_pk_mul_f32 v[80:81], v[52:53], s[2:3] op_sel_hi:[1,0]
	v_mov_b32_dpp v79, v79 row_shl:14 row_mask:0xf bank_mask:0xf bound_ctrl:1
	v_exp_f32_e32 v80, v80
	v_exp_f32_e32 v81, v81
	v_cvt_pk_bf16_f32 v50, v50, v51
	s_nop 0
	v_pk_add_f32 v[80:81], v[80:81], 1.0 op_sel_hi:[1,0]
	s_nop 0
	v_rcp_f32_e32 v80, v80
	v_rcp_f32_e32 v81, v81
	s_nop 0
	v_pk_mul_f32 v[52:53], v[52:53], v[80:81]
	v_mov_b32_dpp v80, v48 row_shr:2 row_mask:0xf bank_mask:0xf bound_ctrl:1
	v_mov_b32_dpp v81, v49 row_shr:2 row_mask:0xf bank_mask:0xf bound_ctrl:1
	v_pk_mul_f32 v[52:53], v[56:57], v[52:53]
	v_mov_b32_dpp v56, v48 row_shr:1 row_mask:0xf bank_mask:0xf bound_ctrl:1
	v_mov_b32_dpp v57, v49 row_shr:1 row_mask:0xf bank_mask:0xf bound_ctrl:1
	v_pk_add_f32 v[78:79], v[80:81], v[78:79]
	v_pk_add_f32 v[56:57], v[56:57], v[82:83]
	v_pk_fma_f32 v[78:79], v[70:71], v[78:79], v[74:75]
	v_mov_b32_dpp v80, v62 row_shl:15 row_mask:0xf bank_mask:0xf bound_ctrl:1
	v_pk_fma_f32 v[56:57], v[58:59], v[56:57], v[78:79]
	v_mov_b32_dpp v81, v63 row_shl:15 row_mask:0xf bank_mask:0xf bound_ctrl:1
	v_pk_fma_f32 v[56:57], v[66:67], v[48:49], v[56:57]
	v_mov_b32_dpp v62, v62 row_shl:14 row_mask:0xf bank_mask:0xf bound_ctrl:1
	v_pk_mul_f32 v[78:79], v[56:57], s[2:3] op_sel_hi:[1,0]
	v_mov_b32_dpp v63, v63 row_shl:14 row_mask:0xf bank_mask:0xf bound_ctrl:1
	v_exp_f32_e32 v78, v78
	v_exp_f32_e32 v79, v79
	v_add_u32_e32 v82, 16, v122
	v_cvt_pk_bf16_f32 v51, v52, v53
	v_pk_add_f32 v[78:79], v[78:79], 1.0 op_sel_hi:[1,0]
	s_nop 0
	v_rcp_f32_e32 v78, v78
	v_rcp_f32_e32 v79, v79
	s_nop 0
	v_pk_mul_f32 v[56:57], v[56:57], v[78:79]
	v_mov_b32_dpp v78, v46 row_shr:2 row_mask:0xf bank_mask:0xf bound_ctrl:1
	v_mov_b32_dpp v79, v47 row_shr:2 row_mask:0xf bank_mask:0xf bound_ctrl:1
	v_pk_mul_f32 v[42:43], v[42:43], v[56:57]
	v_mov_b32_dpp v56, v46 row_shr:1 row_mask:0xf bank_mask:0xf bound_ctrl:1
	v_mov_b32_dpp v57, v47 row_shr:1 row_mask:0xf bank_mask:0xf bound_ctrl:1
	v_pk_add_f32 v[62:63], v[78:79], v[62:63]
	v_pk_add_f32 v[56:57], v[56:57], v[80:81]
	v_pk_fma_f32 v[62:63], v[72:73], v[62:63], v[76:77]
	v_cvt_pk_bf16_f32 v52, v42, v43
	v_mov_b64_e32 v[42:43], s[0:1]
	v_pk_fma_f32 v[56:57], v[60:61], v[56:57], v[62:63]
	s_nop 0
	v_pk_fma_f32 v[56:57], v[68:69], v[46:47], v[56:57]
	s_nop 0
	v_pk_mul_f32 v[62:63], v[56:57], s[2:3] op_sel_hi:[1,0]
	s_nop 0
	v_exp_f32_e32 v62, v62
	v_exp_f32_e32 v63, v63
	s_nop 0
	v_pk_add_f32 v[62:63], v[62:63], 1.0 op_sel_hi:[1,0]
	s_nop 0
	v_rcp_f32_e32 v62, v62
	v_rcp_f32_e32 v63, v63
	s_nop 0
	v_pk_mul_f32 v[56:57], v[56:57], v[62:63]
	s_nop 0
	v_pk_mul_f32 v[44:45], v[44:45], v[56:57]
	v_cvt_pk_bf16_f32 v53, v44, v45
	v_mad_i64_i32 v[44:45], s[0:1], v82, s93, v[42:43]
	v_lshl_add_u64 v[44:45], v[44:45], 0, v[154:155]
	global_store_dwordx4 v[44:45], v[50:53], off sc1
	ds_read_b32 v50, v223 offset:384
	s_waitcnt lgkmcnt(0)
; __device__ __forceinline__ unsigned pk2(float lo, float hi) { unsigned r; asm volatile("v_cvt_pk_bf16_f32 %0, %1, %2" : "=v"(r) : "v"(lo), "v"(hi)); return r; }
; template <int CTRL> __device__ __forceinline__ float dppz(float x) { return __builtin_bit_cast(float, __builtin_amdgcn_update_dpp(0, __builtin_bit_cast(int, x), CTRL, 0xf, 0xf, true)); }
;     __device__ __forceinline__ void fast(const f32x4 (&acc)[2][2][4][2], const pg8::Unit& u, int wr, int wc, int fr, int fq, RsCache& rsc) const {
;     ...
;             for (int m = 0; m < 4; ++m) {
;                 const int row = rowb + m * 16 + fr; const float s = rsc.tab[ai * 64 + m * 16 + fr]; const f32x2 s2 = (f32x2){s, s};
;                 f32x2 g[4], o[4], v[4];
; #pragma unroll
;                 for (int cp = 0; cp < 4; ++cp) { const int n = cp >> 1, e0 = (cp & 1) * 2;
;                     g[cp] = (f32x2){acc[ai][0][m][n][e0], acc[ai][0][m][n][e0 + 1]} * s2; v[cp] = (f32x2){acc[ai][1][m][n][e0], acc[ai][1][m][n][e0 + 1]} * s2; }
; #pragma unroll
;                 for (int cp = 0; cp < 4; ++cp) {
;                     f32x2 p1 = (f32x2){dppz<0x111>(g[cp].x), dppz<0x111>(g[cp].y)}, p2 = (f32x2){dppz<0x112>(g[cp].x), dppz<0x112>(g[cp].y)};
;                     if (m > 0) { p1 += (f32x2){dppz<0x10F>(gp[cp].x), dppz<0x10F>(gp[cp].y)}; p2 += (f32x2){dppz<0x10E>(gp[cp].x), dppz<0x10E>(gp[cp].y)}; }
;                     const f32x2 gv = bb[cp] + w0[cp] * p2 + w1[cp] * p1 + w2[cp] * g[cp];
;                     const f32x2 ea = gv * (-1.44269504089f);
;                     f32x2 ex; ex.x = __builtin_amdgcn_exp2f(ea.x); ex.y = __builtin_amdgcn_exp2f(ea.y);
;                     const f32x2 dn = ex + 1.0f;
;                     f32x2 rc; rc.x = __builtin_amdgcn_rcpf(dn.x); rc.y = __builtin_amdgcn_rcpf(dn.y);
;                     o[cp] = (gv * rc) * v[cp];
;                 }
;                 if (m > 0 || fr >= 2) { uint4 w; w.x = pk2(o[0].x, o[0].y); w.y = pk2(o[1].x, o[1].y); w.z = pk2(o[2].x, o[2].y); w.w = pk2(o[3].x, o[3].y); *(uint4*)(act + (size_t)row * FH + ch) = w; }
	v_pk_mul_f32 v[44:45], v[38:39], v[50:51] op_sel_hi:[1,0]
	v_pk_mul_f32 v[38:39], v[40:41], v[50:51] op_sel_hi:[1,0]
	s_nop 0
	v_mov_b32_dpp v40, v44 row_shr:2 row_mask:0xf bank_mask:0xf bound_ctrl:1
	v_mov_b32_dpp v41, v45 row_shr:2 row_mask:0xf bank_mask:0xf bound_ctrl:1
	v_pk_mul_f32 v[52:53], v[30:31], v[50:51] op_sel_hi:[1,0]
	v_pk_mul_f32 v[32:33], v[32:33], v[50:51] op_sel_hi:[1,0]
	v_pk_mul_f32 v[30:31], v[34:35], v[50:51] op_sel_hi:[1,0]
	v_pk_mul_f32 v[34:35], v[26:27], v[50:51] op_sel_hi:[1,0]
	v_pk_mul_f32 v[26:27], v[36:37], v[50:51] op_sel_hi:[1,0]
	v_pk_mul_f32 v[28:29], v[28:29], v[50:51] op_sel_hi:[1,0]
	v_mov_b32_dpp v36, v44 row_shr:1 row_mask:0xf bank_mask:0xf bound_ctrl:1
	v_mov_b32_dpp v37, v45 row_shr:1 row_mask:0xf bank_mask:0xf bound_ctrl:1
	v_mov_b32_dpp v40, v64 row_shl:14 row_mask:0xf bank_mask:0xf
	v_mov_b32_dpp v41, v65 row_shl:14 row_mask:0xf bank_mask:0xf
	v_mov_b32_dpp v36, v64 row_shl:15 row_mask:0xf bank_mask:0xf
	v_mov_b32_dpp v37, v65 row_shl:15 row_mask:0xf bank_mask:0xf
	v_pk_fma_f32 v[40:41], v[90:91], v[40:41], v[102:103]
	v_mov_b32_dpp v50, v38 row_shr:2 row_mask:0xf bank_mask:0xf bound_ctrl:1
	v_pk_fma_f32 v[36:37], v[94:95], v[36:37], v[40:41]
	v_mov_b32_dpp v51, v39 row_shr:2 row_mask:0xf bank_mask:0xf bound_ctrl:1
	v_pk_fma_f32 v[36:37], v[98:99], v[44:45], v[36:37]
	s_nop 0
	v_pk_mul_f32 v[40:41], v[36:37], s[2:3] op_sel_hi:[1,0]
	s_nop 0
	v_exp_f32_e32 v40, v40
	v_exp_f32_e32 v41, v41
	s_nop 0
	v_pk_add_f32 v[40:41], v[40:41], 1.0 op_sel_hi:[1,0]
	s_nop 0
	v_rcp_f32_e32 v40, v40
	v_rcp_f32_e32 v41, v41
	s_nop 0
	v_pk_mul_f32 v[36:37], v[36:37], v[40:41]
	s_nop 0
	v_pk_mul_f32 v[36:37], v[52:53], v[36:37]
	v_mov_b32_dpp v52, v54 row_shl:15 row_mask:0xf bank_mask:0xf bound_ctrl:1
	v_mov_b32_dpp v53, v55 row_shl:15 row_mask:0xf bank_mask:0xf bound_ctrl:1
	v_mov_b32_dpp v40, v38 row_shr:1 row_mask:0xf bank_mask:0xf bound_ctrl:1
	v_mov_b32_dpp v41, v39 row_shr:1 row_mask:0xf bank_mask:0xf bound_ctrl:1
	v_mov_b32_dpp v50, v54 row_shl:14 row_mask:0xf bank_mask:0xf
	v_mov_b32_dpp v51, v55 row_shl:14 row_mask:0xf bank_mask:0xf
	v_pk_add_f32 v[40:41], v[40:41], v[52:53]
	v_pk_fma_f32 v[50:51], v[92:93], v[50:51], v[104:105]
	v_mov_b32_dpp v52, v48 row_shl:15 row_mask:0xf bank_mask:0xf bound_ctrl:1
	v_pk_fma_f32 v[40:41], v[96:97], v[40:41], v[50:51]
	v_mov_b32_dpp v53, v49 row_shl:15 row_mask:0xf bank_mask:0xf bound_ctrl:1
	v_pk_fma_f32 v[40:41], v[100:101], v[38:39], v[40:41]
	v_mov_b32_dpp v48, v48 row_shl:14 row_mask:0xf bank_mask:0xf bound_ctrl:1
	v_pk_mul_f32 v[50:51], v[40:41], s[2:3] op_sel_hi:[1,0]
	v_mov_b32_dpp v49, v49 row_shl:14 row_mask:0xf bank_mask:0xf bound_ctrl:1
	v_exp_f32_e32 v50, v50
	v_exp_f32_e32 v51, v51
	s_nop 0
	v_pk_add_f32 v[50:51], v[50:51], 1.0 op_sel_hi:[1,0]
	s_nop 0
	v_rcp_f32_e32 v50, v50
	v_rcp_f32_e32 v51, v51
	s_nop 0
	v_pk_mul_f32 v[40:41], v[40:41], v[50:51]
	v_mov_b32_dpp v50, v30 row_shr:2 row_mask:0xf bank_mask:0xf bound_ctrl:1
	v_mov_b32_dpp v51, v31 row_shr:2 row_mask:0xf bank_mask:0xf bound_ctrl:1
	v_pk_mul_f32 v[40:41], v[32:33], v[40:41]
	v_mov_b32_dpp v32, v30 row_shr:1 row_mask:0xf bank_mask:0xf bound_ctrl:1
	v_mov_b32_dpp v33, v31 row_shr:1 row_mask:0xf bank_mask:0xf bound_ctrl:1
	v_pk_add_f32 v[48:49], v[50:51], v[48:49]
	v_pk_add_f32 v[32:33], v[32:33], v[52:53]
	v_pk_fma_f32 v[48:49], v[70:71], v[48:49], v[74:75]
	v_mov_b32_dpp v50, v46 row_shl:15 row_mask:0xf bank_mask:0xf bound_ctrl:1
	v_pk_fma_f32 v[32:33], v[58:59], v[32:33], v[48:49]
	v_mov_b32_dpp v51, v47 row_shl:15 row_mask:0xf bank_mask:0xf bound_ctrl:1
	v_pk_fma_f32 v[32:33], v[66:67], v[30:31], v[32:33]
	v_mov_b32_dpp v46, v46 row_shl:14 row_mask:0xf bank_mask:0xf bound_ctrl:1
	v_pk_mul_f32 v[48:49], v[32:33], s[2:3] op_sel_hi:[1,0]
	v_mov_b32_dpp v47, v47 row_shl:14 row_mask:0xf bank_mask:0xf bound_ctrl:1
	v_exp_f32_e32 v48, v48
	v_exp_f32_e32 v49, v49
	v_add_u32_e32 v52, 32, v122
	v_pk_add_f32 v[48:49], v[48:49], 1.0 op_sel_hi:[1,0]
	s_nop 0
	v_rcp_f32_e32 v48, v48
	v_rcp_f32_e32 v49, v49
	s_nop 0
	v_pk_mul_f32 v[32:33], v[32:33], v[48:49]
	v_mov_b32_dpp v48, v26 row_shr:2 row_mask:0xf bank_mask:0xf bound_ctrl:1
	v_mov_b32_dpp v49, v27 row_shr:2 row_mask:0xf bank_mask:0xf bound_ctrl:1
	v_pk_mul_f32 v[34:35], v[34:35], v[32:33]
	v_mov_b32_dpp v32, v26 row_shr:1 row_mask:0xf bank_mask:0xf bound_ctrl:1
	v_mov_b32_dpp v33, v27 row_shr:1 row_mask:0xf bank_mask:0xf bound_ctrl:1
	v_pk_add_f32 v[46:47], v[48:49], v[46:47]
	v_pk_add_f32 v[32:33], v[32:33], v[50:51]
	v_pk_fma_f32 v[46:47], v[72:73], v[46:47], v[76:77]
	s_nop 0
	v_pk_fma_f32 v[32:33], v[60:61], v[32:33], v[46:47]
	s_nop 0
	v_pk_fma_f32 v[32:33], v[68:69], v[26:27], v[32:33]
	s_nop 0
	v_pk_mul_f32 v[46:47], v[32:33], s[2:3] op_sel_hi:[1,0]
	s_nop 0
	v_exp_f32_e32 v46, v46
	v_exp_f32_e32 v47, v47
	s_nop 0
	v_pk_add_f32 v[46:47], v[46:47], 1.0 op_sel_hi:[1,0]
	s_nop 0
	v_rcp_f32_e32 v46, v46
	v_rcp_f32_e32 v47, v47
	s_nop 0
	v_pk_mul_f32 v[32:33], v[32:33], v[46:47]
	s_nop 0
	v_pk_mul_f32 v[28:29], v[28:29], v[32:33]
	v_cvt_pk_bf16_f32 v32, v36, v37
	v_cvt_pk_bf16_f32 v33, v40, v41
	v_cvt_pk_bf16_f32 v34, v34, v35
	v_cvt_pk_bf16_f32 v35, v28, v29
	v_mad_i64_i32 v[28:29], s[0:1], v52, s93, v[42:43]
	v_lshl_add_u64 v[28:29], v[28:29], 0, v[154:155]
	s_cmp_lg_u64 s[4:5], 0
	s_cbranch_scc1 .Lwt_1
	global_store_dwordx4 v[28:29], v[32:35], off
;     __device__ __forceinline__ void fast(const f32x4 (&acc)[2][2][4][2], const pg8::Unit& u, int wr, int wc, int fr, int fq, RsCache& rsc) const {
;     ...
;             for (int m = 0; m < 4; ++m) {
;                 const int row = rowb + m * 16 + fr; const float s = rsc.tab[ai * 64 + m * 16 + fr]; const f32x2 s2 = (f32x2){s, s};
;                 f32x2 g[4], o[4], v[4];
; #pragma unroll
;                 for (int cp = 0; cp < 4; ++cp) { const int n = cp >> 1, e0 = (cp & 1) * 2;
;                     g[cp] = (f32x2){acc[ai][0][m][n][e0], acc[ai][0][m][n][e0 + 1]} * s2; v[cp] = (f32x2){acc[ai][1][m][n][e0], acc[ai][1][m][n][e0 + 1]} * s2; }
; #pragma unroll
;                 for (int cp = 0; cp < 4; ++cp) {
;                     f32x2 p1 = (f32x2){dppz<0x111>(g[cp].x), dppz<0x111>(g[cp].y)}, p2 = (f32x2){dppz<0x112>(g[cp].x), dppz<0x112>(g[cp].y)};
;                     if (m > 0) { p1 += (f32x2){dppz<0x10F>(gp[cp].x), dppz<0x10F>(gp[cp].y)}; p2 += (f32x2){dppz<0x10E>(gp[cp].x), dppz<0x10E>(gp[cp].y)}; }
;                     const f32x2 gv = bb[cp] + w0[cp] * p2 + w1[cp] * p1 + w2[cp] * g[cp];
;                     const f32x2 ea = gv * (-1.44269504089f);
;                     f32x2 ex; ex.x = __builtin_amdgcn_exp2f(ea.x); ex.y = __builtin_amdgcn_exp2f(ea.y);
;                     const f32x2 dn = ex + 1.0f;
;                     f32x2 rc; rc.x = __builtin_amdgcn_rcpf(dn.x); rc.y = __builtin_amdgcn_rcpf(dn.y);
;                     o[cp] = (gv * rc) * v[cp];
;                 }
;                 if (m > 0 || fr >= 2) { uint4 w; w.x = pk2(o[0].x, o[0].y); w.y = pk2(o[1].x, o[1].y); w.z = pk2(o[2].x, o[2].y); w.w = pk2(o[3].x, o[3].y); *(uint4*)(act + (size_t)row * FH + ch) = w; }
;                 if (m == 0 && fr < 2) { uint4 w; w.x = pk2(g[0].x, g[0].y); w.y = pk2(g[1].x, g[1].y); w.z = pk2(g[2].x, g[2].y); w.w = pk2(g[3].x, g[3].y); *(uint4*)(sideg + ((size_t)blk * 4 + fr) * FH + ch) = w;
;                     uint4 q; q.x = pk2(v[0].x, v[0].y); q.y = pk2(v[1].x, v[1].y); q.z = pk2(v[2].x, v[2].y); q.w = pk2(v[3].x, v[3].y); *(uint4*)(sidev + ((size_t)blk * 2 + fr) * FH + ch) = q; }
;                 if (m == 3 && fr >= 14) { uint4 w; w.x = pk2(g[0].x, g[0].y); w.y = pk2(g[1].x, g[1].y); w.z = pk2(g[2].x, g[2].y); w.w = pk2(g[3].x, g[3].y); *(uint4*)(sideg + ((size_t)blk * 4 + 2 + (fr - 14)) * FH + ch) = w; }
.Lwb_1:
	ds_read_b32 v28, v223 offset:448
	s_waitcnt lgkmcnt(0)
	v_pk_mul_f32 v[22:23], v[22:23], v[28:29] op_sel_hi:[1,0]
	v_pk_mul_f32 v[32:33], v[14:15], v[28:29] op_sel_hi:[1,0]
	v_pk_mul_f32 v[14:15], v[24:25], v[28:29] op_sel_hi:[1,0]
	v_pk_mul_f32 v[24:25], v[16:17], v[28:29] op_sel_hi:[1,0]
	v_pk_mul_f32 v[16:17], v[18:19], v[28:29] op_sel_hi:[1,0]
	v_pk_mul_f32 v[18:19], v[10:11], v[28:29] op_sel_hi:[1,0]
	v_pk_mul_f32 v[10:11], v[20:21], v[28:29] op_sel_hi:[1,0]
	v_pk_mul_f32 v[12:13], v[12:13], v[28:29] op_sel_hi:[1,0]
	v_mov_b32_dpp v28, v22 row_shr:2 row_mask:0xf bank_mask:0xf bound_ctrl:1
	v_mov_b32_dpp v29, v23 row_shr:2 row_mask:0xf bank_mask:0xf bound_ctrl:1
	v_mov_b32_dpp v20, v22 row_shr:1 row_mask:0xf bank_mask:0xf bound_ctrl:1
	v_mov_b32_dpp v21, v23 row_shr:1 row_mask:0xf bank_mask:0xf bound_ctrl:1
	v_mov_b32_dpp v28, v44 row_shl:14 row_mask:0xf bank_mask:0xf
	v_mov_b32_dpp v29, v45 row_shl:14 row_mask:0xf bank_mask:0xf
	v_mov_b32_dpp v20, v44 row_shl:15 row_mask:0xf bank_mask:0xf
	v_mov_b32_dpp v21, v45 row_shl:15 row_mask:0xf bank_mask:0xf
	v_pk_fma_f32 v[28:29], v[90:91], v[28:29], v[102:103]
	v_pk_fma_f32 v[20:21], v[94:95], v[20:21], v[28:29]
	v_pk_fma_f32 v[20:21], v[98:99], v[22:23], v[20:21]
	v_pk_mul_f32 v[28:29], v[20:21], s[2:3] op_sel_hi:[1,0]
	v_exp_f32_e32 v28, v28
	v_exp_f32_e32 v29, v29
	s_nop 0
	v_pk_add_f32 v[28:29], v[28:29], 1.0 op_sel_hi:[1,0]
	s_nop 0
	v_rcp_f32_e32 v28, v28
	v_rcp_f32_e32 v29, v29
	s_nop 0
	v_pk_mul_f32 v[20:21], v[20:21], v[28:29]
	s_nop 0
	v_pk_mul_f32 v[20:21], v[32:33], v[20:21]
	v_mov_b32_dpp v32, v14 row_shr:2 row_mask:0xf bank_mask:0xf bound_ctrl:1
	v_mov_b32_dpp v33, v15 row_shr:2 row_mask:0xf bank_mask:0xf bound_ctrl:1
	v_mov_b32_dpp v28, v14 row_shr:1 row_mask:0xf bank_mask:0xf bound_ctrl:1
	v_mov_b32_dpp v29, v15 row_shr:1 row_mask:0xf bank_mask:0xf bound_ctrl:1
	v_mov_b32_dpp v32, v38 row_shl:14 row_mask:0xf bank_mask:0xf
	v_mov_b32_dpp v33, v39 row_shl:14 row_mask:0xf bank_mask:0xf
	v_mov_b32_dpp v28, v38 row_shl:15 row_mask:0xf bank_mask:0xf
	v_mov_b32_dpp v29, v39 row_shl:15 row_mask:0xf bank_mask:0xf
	v_pk_fma_f32 v[32:33], v[92:93], v[32:33], v[104:105]
	v_mov_b32_dpp v34, v30 row_shl:15 row_mask:0xf bank_mask:0xf bound_ctrl:1
	v_pk_fma_f32 v[28:29], v[96:97], v[28:29], v[32:33]
	v_mov_b32_dpp v35, v31 row_shl:15 row_mask:0xf bank_mask:0xf bound_ctrl:1
	v_pk_fma_f32 v[28:29], v[100:101], v[14:15], v[28:29]
	v_mov_b32_dpp v30, v30 row_shl:14 row_mask:0xf bank_mask:0xf bound_ctrl:1
	v_pk_mul_f32 v[32:33], v[28:29], s[2:3] op_sel_hi:[1,0]
	v_mov_b32_dpp v31, v31 row_shl:14 row_mask:0xf bank_mask:0xf bound_ctrl:1
	v_exp_f32_e32 v32, v32
	v_exp_f32_e32 v33, v33
	s_nop 0
	v_pk_add_f32 v[32:33], v[32:33], 1.0 op_sel_hi:[1,0]
	s_nop 0
	v_rcp_f32_e32 v32, v32
	v_rcp_f32_e32 v33, v33
	s_nop 0
	v_pk_mul_f32 v[28:29], v[28:29], v[32:33]
	v_mov_b32_dpp v32, v16 row_shr:2 row_mask:0xf bank_mask:0xf bound_ctrl:1
	v_mov_b32_dpp v33, v17 row_shr:2 row_mask:0xf bank_mask:0xf bound_ctrl:1
	v_pk_mul_f32 v[24:25], v[24:25], v[28:29]
	v_mov_b32_dpp v28, v16 row_shr:1 row_mask:0xf bank_mask:0xf bound_ctrl:1
	v_mov_b32_dpp v29, v17 row_shr:1 row_mask:0xf bank_mask:0xf bound_ctrl:1
	v_pk_add_f32 v[30:31], v[32:33], v[30:31]
	v_pk_add_f32 v[28:29], v[28:29], v[34:35]
	v_pk_fma_f32 v[30:31], v[70:71], v[30:31], v[74:75]
	v_mov_b32_dpp v32, v26 row_shl:15 row_mask:0xf bank_mask:0xf bound_ctrl:1
	v_pk_fma_f32 v[28:29], v[58:59], v[28:29], v[30:31]
	v_mov_b32_dpp v33, v27 row_shl:15 row_mask:0xf bank_mask:0xf bound_ctrl:1
	v_pk_fma_f32 v[28:29], v[66:67], v[16:17], v[28:29]
	v_mov_b32_dpp v26, v26 row_shl:14 row_mask:0xf bank_mask:0xf bound_ctrl:1
	v_pk_mul_f32 v[30:31], v[28:29], s[2:3] op_sel_hi:[1,0]
	v_mov_b32_dpp v27, v27 row_shl:14 row_mask:0xf bank_mask:0xf bound_ctrl:1
	v_exp_f32_e32 v30, v30
	v_exp_f32_e32 v31, v31
	v_add_u32_e32 v34, 48, v122
	v_pk_add_f32 v[30:31], v[30:31], 1.0 op_sel_hi:[1,0]
	s_nop 0
	v_rcp_f32_e32 v30, v30
	v_rcp_f32_e32 v31, v31
	s_nop 0
	v_pk_mul_f32 v[28:29], v[28:29], v[30:31]
	v_mov_b32_dpp v30, v10 row_shr:2 row_mask:0xf bank_mask:0xf bound_ctrl:1
	v_mov_b32_dpp v31, v11 row_shr:2 row_mask:0xf bank_mask:0xf bound_ctrl:1
	v_pk_mul_f32 v[28:29], v[18:19], v[28:29]
	v_mov_b32_dpp v18, v10 row_shr:1 row_mask:0xf bank_mask:0xf bound_ctrl:1
	v_mov_b32_dpp v19, v11 row_shr:1 row_mask:0xf bank_mask:0xf bound_ctrl:1
	v_pk_add_f32 v[26:27], v[30:31], v[26:27]
	v_pk_add_f32 v[18:19], v[18:19], v[32:33]
	v_pk_fma_f32 v[26:27], v[72:73], v[26:27], v[76:77]
	s_nop 0
	v_pk_fma_f32 v[18:19], v[60:61], v[18:19], v[26:27]
	s_nop 0
	v_pk_fma_f32 v[18:19], v[68:69], v[10:11], v[18:19]
	s_nop 0
	v_pk_mul_f32 v[26:27], v[18:19], s[2:3] op_sel_hi:[1,0]
	s_nop 0
	v_exp_f32_e32 v26, v26
	v_exp_f32_e32 v27, v27
	s_nop 0
	v_pk_add_f32 v[26:27], v[26:27], 1.0 op_sel_hi:[1,0]
	s_nop 0
	v_rcp_f32_e32 v26, v26
	v_rcp_f32_e32 v27, v27
	s_nop 0
	v_pk_mul_f32 v[18:19], v[18:19], v[26:27]
	s_nop 0
	v_pk_mul_f32 v[12:13], v[12:13], v[18:19]
	v_cvt_pk_bf16_f32 v18, v20, v21
	v_cvt_pk_bf16_f32 v19, v24, v25
	v_cvt_pk_bf16_f32 v20, v28, v29
	s_nop 0
	v_cvt_pk_bf16_f32 v21, v12, v13
	v_mad_i64_i32 v[12:13], s[0:1], v34, s93, v[42:43]
	v_lshl_add_u64 v[12:13], v[12:13], 0, v[154:155]
	s_cmp_lg_u64 s[4:5], 0
	s_cbranch_scc1 .Lwt_2
	global_store_dwordx4 v[12:13], v[18:21], off
.Lwb_2:
	s_and_saveexec_b64 s[0:1], vcc
	s_cbranch_execz .LBB0_278
	v_readlane_b32 s2, v254, 1
	v_readlane_b32 s3, v254, 2
	v_lshl_add_u64 v[18:19], s[6:7], 0, v[156:157]
	v_cvt_pk_bf16_f32 v12, v22, v23
	v_cvt_pk_bf16_f32 v13, v14, v15
	v_cvt_pk_bf16_f32 v14, v16, v17
	v_cvt_pk_bf16_f32 v15, v10, v11
	s_nop 0
	v_mov_b64_e32 v[10:11], s[2:3]
	v_mad_u64_u32 v[10:11], s[2:3], v18, s93, v[10:11]
	v_mad_i32_i24 v11, v19, s93, v11
	v_lshl_add_u64 v[10:11], v[184:185], 1, v[10:11]
	s_cmp_lg_u64 s[4:5], 0
	s_cbranch_scc1 .Lwt_3
	global_store_dwordx4 v[10:11], v[12:15], off
.Lwb_3:
.LBB0_278:
	s_or_b64 exec, exec, s[0:1]
	s_and_b64 vcc, exec, s[4:5]
	s_mov_b64 s[0:1], -1
	s_cbranch_vccnz .LBB0_251
	v_readlane_b32 s0, v255, 14
	v_readlane_b32 s1, v255, 15
	s_andn2_b64 vcc, exec, s[0:1]
	s_cbranch_vccnz .LBB0_250
	s_barrier
	s_branch .LBB0_250
.Lwt_1:
	global_store_dwordx4 v[28:29], v[32:35], off sc1
	s_branch .Lwb_1
.Lwt_2:
	global_store_dwordx4 v[12:13], v[18:21], off sc1
	s_branch .Lwb_2
.Lwt_3:
	global_store_dwordx4 v[10:11], v[12:15], off sc1
	s_branch .Lwb_3

; __device__ __forceinline__ unsigned pk2(float lo, float hi) { unsigned r; asm volatile("v_cvt_pk_bf16_f32 %0, %1, %2" : "=v"(r) : "v"(lo), "v"(hi)); return r; }
;     __device__ __forceinline__ void fast(const f32x4 (&acc)[2][2][4][2], const pg8::Unit& u, int wr, int wc, int fr, int fq, RsCache& rsc) const {
;         asm volatile("" : "+v"(fr), "+v"(fq));
;         rs_cache_fill(rsc, rs, u.pm, wr, fq * 16 + fr);
;         const int row0 = u.pm * 256 + wr * 64 + fr;
;         if (u.pn < 8) {
;             const int cb = 1024 + u.pn * 128 + wc * 32 + 8 * fq;
; #pragma unroll
;             for (int ai = 0; ai < 2; ++ai)
; #pragma unroll
;                 for (int m = 0; m < 4; ++m) { const int row = row0 + ai * 128 + m * 16; const float s = rsc.tab[ai * 64 + m * 16 + fr]; const float s2 = s * s;
;                     const f32x4 v0 = acc[ai][0][m][0] * acc[ai][1][m][0] * s2, v1 = acc[ai][0][m][1] * acc[ai][1][m][1] * s2;
;                     u32x4 w; w.x = pk2(v0[0], v0[1]); w.y = pk2(v0[2], v0[3]); w.z = pk2(v1[0], v1[1]); w.w = pk2(v1[2], v1[3]);
;                     *(u32x4*)(out + (size_t)row * ldc + cb) = w;
;                     asm volatile("" ::: "memory"); }
;         } else {
;             const int cb = (u.pn - 8) * 256 + wc * 32 + 8 * fq;
; #pragma unroll
;             for (int ai = 0; ai < 2; ++ai)
; #pragma unroll
;                 for (int m = 0; m < 4; ++m) { const int row = row0 + ai * 128 + m * 16; const float s = rsc.tab[ai * 64 + m * 16 + fr]; bf16_t* rowp = out + (size_t)row * ldc + cb;
; #pragma unroll
;                     for (int bj = 0; bj < 2; ++bj) { const f32x4 v0 = acc[ai][bj][m][0] * s, v1 = acc[ai][bj][m][1] * s;
;                         u32x4 w; w.x = pk2(v0[0], v0[1]); w.y = pk2(v0[2], v0[3]); w.z = pk2(v1[0], v1[1]); w.w = pk2(v1[2], v1[3]);
;                         *(u32x4*)(rowp + bj * 128) = w; }
;                     asm volatile("" ::: "memory"); }
.LBB0_304:
	v_lshl_add_u32 v156, v147, 2, s89
	ds_read_b32 v148, v156
	s_add_i32 s0, s36, s92
	v_add_u32_e32 v180, s0, v147
	v_lshlrev_b32_e32 v146, 3, v146
	v_ashrrev_i32_e32 v150, 31, v180
	v_add_u32_e32 v177, 16, v180
	v_add_u32_e32 v169, 32, v180
	v_add_u32_e32 v166, 48, v180
	v_add_u32_e32 v163, 0x80, v180
	v_add_u32_e32 v160, 0x90, v180
	v_add_u32_e32 v157, 0xa0, v180
	s_cmp_gt_i32 s3, 7
	s_mov_b64 s[0:1], -1
	v_ashrrev_i32_e32 v147, 31, v146
	v_mul_lo_u32 v181, s19, v180
	v_mul_lo_u32 v182, s18, v150
	v_ashrrev_i32_e32 v179, 31, v177
	v_mul_lo_u32 v178, s19, v177
	v_ashrrev_i32_e32 v176, 31, v169
	v_mul_lo_u32 v175, s19, v169
	v_ashrrev_i32_e32 v168, 31, v166
	v_mul_lo_u32 v167, s19, v166
	v_ashrrev_i32_e32 v165, 31, v163
	v_mul_lo_u32 v164, s19, v163
	v_ashrrev_i32_e32 v162, 31, v160
	v_mul_lo_u32 v161, s19, v160
	v_ashrrev_i32_e32 v159, 31, v157
	v_mul_lo_u32 v158, s19, v157
	v_add_u32_e32 v155, 0xb0, v180
	s_cbranch_scc0 .LBB0_307
	s_lshl_b32 s36, s3, 8
	v_mad_u64_u32 v[150:151], s[0:1], s18, v180, 0
	v_add3_u32 v151, v151, v182, v181
	s_or_b32 s36, s8, s36
	v_lshl_add_u64 v[172:173], v[150:151], 1, s[20:21]
	v_lshl_add_u64 v[150:151], s[36:37], 0, v[146:147]
	v_lshlrev_b64 v[150:151], 1, v[150:151]
	s_waitcnt lgkmcnt(0)
	v_pk_mul_f32 v[186:187], v[136:137], v[148:149] op_sel_hi:[1,0]
	v_pk_mul_f32 v[184:185], v[134:135], v[148:149] op_sel_hi:[1,0]
	v_lshl_add_u64 v[172:173], v[172:173], 0, v[150:151]
	v_pk_mul_f32 v[188:189], v[132:133], v[148:149] op_sel_hi:[1,0]
	v_pk_mul_f32 v[190:191], v[130:131], v[148:149] op_sel_hi:[1,0]
	v_cvt_pk_bf16_f32 v184, v184, v185
	v_cvt_pk_bf16_f32 v185, v186, v187
	v_mul_lo_u32 v183, s19, v155
	v_cvt_pk_bf16_f32 v186, v190, v191
	v_cvt_pk_bf16_f32 v187, v188, v189
	s_cmp_lg_u64 s[4:5], 0
	s_cbranch_scc1 .Lwt_4
	global_store_dwordx4 v[172:173], v[184:187], off offset:-4096
.Lwb_4:
	v_pk_mul_f32 v[188:189], v[124:125], v[148:149] op_sel_hi:[1,0]
	v_pk_mul_f32 v[190:191], v[122:123], v[148:149] op_sel_hi:[1,0]
	v_pk_mul_f32 v[186:187], v[128:129], v[148:149] op_sel_hi:[1,0]
	v_pk_mul_f32 v[184:185], v[126:127], v[148:149] op_sel_hi:[1,0]
	s_nop 0
	v_cvt_pk_bf16_f32 v184, v184, v185
	v_cvt_pk_bf16_f32 v185, v186, v187
	v_cvt_pk_bf16_f32 v186, v190, v191
	v_cvt_pk_bf16_f32 v187, v188, v189
	s_cmp_lg_u64 s[4:5], 0
	s_cbranch_scc1 .Lwt_5
	global_store_dwordx4 v[172:173], v[184:187], off offset:-3840
.Lwb_5:
	ds_read_b32 v172, v156 offset:64
	v_mul_lo_u32 v173, s18, v179
	v_mad_u64_u32 v[184:185], s[0:1], s18, v177, 0
	v_add3_u32 v185, v185, v173, v178
	v_lshl_add_u64 v[184:185], v[184:185], 1, s[20:21]
	v_lshl_add_u64 v[188:189], v[184:185], 0, v[150:151]
	s_waitcnt lgkmcnt(0)
	v_pk_mul_f32 v[186:187], v[120:121], v[172:173] op_sel_hi:[1,0]
	v_pk_mul_f32 v[184:185], v[118:119], v[172:173] op_sel_hi:[1,0]
	v_pk_mul_f32 v[190:191], v[116:117], v[172:173] op_sel_hi:[1,0]
	v_pk_mul_f32 v[192:193], v[114:115], v[172:173] op_sel_hi:[1,0]
	v_cvt_pk_bf16_f32 v184, v184, v185
	v_cvt_pk_bf16_f32 v185, v186, v187
	s_nop 0
	v_cvt_pk_bf16_f32 v186, v192, v193
	v_cvt_pk_bf16_f32 v187, v190, v191
	s_cmp_lg_u64 s[4:5], 0
	s_cbranch_scc1 .Lwt_6
	global_store_dwordx4 v[188:189], v[184:187], off offset:-4096
.Lwb_6:
	v_pk_mul_f32 v[190:191], v[108:109], v[172:173] op_sel_hi:[1,0]
	s_nop 0
	v_pk_mul_f32 v[186:187], v[112:113], v[172:173] op_sel_hi:[1,0]
	v_pk_mul_f32 v[184:185], v[110:111], v[172:173] op_sel_hi:[1,0]
	v_pk_mul_f32 v[172:173], v[106:107], v[172:173] op_sel_hi:[1,0]
	v_cvt_pk_bf16_f32 v184, v184, v185
	v_cvt_pk_bf16_f32 v185, v186, v187
	s_nop 0
	v_cvt_pk_bf16_f32 v186, v172, v173
	v_cvt_pk_bf16_f32 v187, v190, v191
	s_cmp_lg_u64 s[4:5], 0
	s_cbranch_scc1 .Lwt_7
	global_store_dwordx4 v[188:189], v[184:187], off offset:-3840
.Lwb_7:
	ds_read_b32 v172, v156 offset:128
	v_mul_lo_u32 v173, s18, v176
	v_mad_u64_u32 v[184:185], s[0:1], s18, v169, 0
	v_add3_u32 v185, v185, v173, v175
	v_lshl_add_u64 v[184:185], v[184:185], 1, s[20:21]
	v_lshl_add_u64 v[188:189], v[184:185], 0, v[150:151]
	s_waitcnt lgkmcnt(0)
	v_pk_mul_f32 v[186:187], v[104:105], v[172:173] op_sel_hi:[1,0]
	v_pk_mul_f32 v[184:185], v[102:103], v[172:173] op_sel_hi:[1,0]
	v_pk_mul_f32 v[190:191], v[100:101], v[172:173] op_sel_hi:[1,0]
	v_pk_mul_f32 v[192:193], v[98:99], v[172:173] op_sel_hi:[1,0]
	v_cvt_pk_bf16_f32 v184, v184, v185
	v_cvt_pk_bf16_f32 v185, v186, v187
	s_nop 0
	v_cvt_pk_bf16_f32 v186, v192, v193
	v_cvt_pk_bf16_f32 v187, v190, v191
	s_cmp_lg_u64 s[4:5], 0
	s_cbranch_scc1 .Lwt_8
	global_store_dwordx4 v[188:189], v[184:187], off offset:-4096
.Lwb_8:
	v_pk_mul_f32 v[190:191], v[92:93], v[172:173] op_sel_hi:[1,0]
	s_nop 0
	v_pk_mul_f32 v[186:187], v[96:97], v[172:173] op_sel_hi:[1,0]
	v_pk_mul_f32 v[184:185], v[94:95], v[172:173] op_sel_hi:[1,0]
	v_pk_mul_f32 v[172:173], v[90:91], v[172:173] op_sel_hi:[1,0]
	v_cvt_pk_bf16_f32 v184, v184, v185
	v_cvt_pk_bf16_f32 v185, v186, v187
	s_nop 0
	v_cvt_pk_bf16_f32 v186, v172, v173
	v_cvt_pk_bf16_f32 v187, v190, v191
	s_cmp_lg_u64 s[4:5], 0
	s_cbranch_scc1 .Lwt_9
	global_store_dwordx4 v[188:189], v[184:187], off offset:-3840
.Lwb_9:
	ds_read_b32 v172, v156 offset:192
	v_mul_lo_u32 v173, s18, v168
	v_mad_u64_u32 v[184:185], s[0:1], s18, v166, 0
	v_add3_u32 v185, v185, v173, v167
	v_lshl_add_u64 v[184:185], v[184:185], 1, s[20:21]
	v_lshl_add_u64 v[188:189], v[184:185], 0, v[150:151]
	s_waitcnt lgkmcnt(0)
	v_pk_mul_f32 v[186:187], v[88:89], v[172:173] op_sel_hi:[1,0]
	v_pk_mul_f32 v[184:185], v[86:87], v[172:173] op_sel_hi:[1,0]
	v_pk_mul_f32 v[190:191], v[84:85], v[172:173] op_sel_hi:[1,0]
	v_pk_mul_f32 v[192:193], v[82:83], v[172:173] op_sel_hi:[1,0]
	v_cvt_pk_bf16_f32 v184, v184, v185
	v_cvt_pk_bf16_f32 v185, v186, v187
	s_nop 0
	v_cvt_pk_bf16_f32 v186, v192, v193
	v_cvt_pk_bf16_f32 v187, v190, v191
	s_cmp_lg_u64 s[4:5], 0
	s_cbranch_scc1 .Lwt_10
	global_store_dwordx4 v[188:189], v[184:187], off offset:-4096
; __device__ __forceinline__ unsigned pk2(float lo, float hi) { unsigned r; asm volatile("v_cvt_pk_bf16_f32 %0, %1, %2" : "=v"(r) : "v"(lo), "v"(hi)); return r; }
;     __device__ __forceinline__ void fast(const f32x4 (&acc)[2][2][4][2], const pg8::Unit& u, int wr, int wc, int fr, int fq, RsCache& rsc) const {
;     ...
;             const int cb = (u.pn - 8) * 256 + wc * 32 + 8 * fq;
; #pragma unroll
;             for (int ai = 0; ai < 2; ++ai)
; #pragma unroll
;                 for (int m = 0; m < 4; ++m) { const int row = row0 + ai * 128 + m * 16; const float s = rsc.tab[ai * 64 + m * 16 + fr]; bf16_t* rowp = out + (size_t)row * ldc + cb;
; #pragma unroll
;                     for (int bj = 0; bj < 2; ++bj) { const f32x4 v0 = acc[ai][bj][m][0] * s, v1 = acc[ai][bj][m][1] * s;
;                         u32x4 w; w.x = pk2(v0[0], v0[1]); w.y = pk2(v0[2], v0[3]); w.z = pk2(v1[0], v1[1]); w.w = pk2(v1[2], v1[3]);
;                         *(u32x4*)(rowp + bj * 128) = w; }
;                     asm volatile("" ::: "memory"); }
.Lwb_10:
	v_pk_mul_f32 v[190:191], v[76:77], v[172:173] op_sel_hi:[1,0]
	s_nop 0
	v_pk_mul_f32 v[186:187], v[80:81], v[172:173] op_sel_hi:[1,0]
	v_pk_mul_f32 v[184:185], v[78:79], v[172:173] op_sel_hi:[1,0]
	v_pk_mul_f32 v[172:173], v[74:75], v[172:173] op_sel_hi:[1,0]
	v_cvt_pk_bf16_f32 v184, v184, v185
	v_cvt_pk_bf16_f32 v185, v186, v187
	s_nop 0
	v_cvt_pk_bf16_f32 v186, v172, v173
	v_cvt_pk_bf16_f32 v187, v190, v191
	s_cmp_lg_u64 s[4:5], 0
	s_cbranch_scc1 .Lwt_11
	global_store_dwordx4 v[188:189], v[184:187], off offset:-3840
.Lwb_11:
	ds_read_b32 v172, v156 offset:256
	v_mul_lo_u32 v173, s18, v165
	v_mad_u64_u32 v[184:185], s[0:1], s18, v163, 0
	v_add3_u32 v185, v185, v173, v164
	v_lshl_add_u64 v[184:185], v[184:185], 1, s[20:21]
	v_lshl_add_u64 v[188:189], v[184:185], 0, v[150:151]
	s_waitcnt lgkmcnt(0)
	v_pk_mul_f32 v[186:187], v[72:73], v[172:173] op_sel_hi:[1,0]
	v_pk_mul_f32 v[184:185], v[70:71], v[172:173] op_sel_hi:[1,0]
	v_pk_mul_f32 v[190:191], v[68:69], v[172:173] op_sel_hi:[1,0]
	v_pk_mul_f32 v[192:193], v[66:67], v[172:173] op_sel_hi:[1,0]
	v_cvt_pk_bf16_f32 v184, v184, v185
	v_cvt_pk_bf16_f32 v185, v186, v187
	s_nop 0
	v_cvt_pk_bf16_f32 v186, v192, v193
	v_cvt_pk_bf16_f32 v187, v190, v191
	s_cmp_lg_u64 s[4:5], 0
	s_cbranch_scc1 .Lwt_12
	global_store_dwordx4 v[188:189], v[184:187], off offset:-4096
.Lwb_12:
	v_pk_mul_f32 v[190:191], v[60:61], v[172:173] op_sel_hi:[1,0]
	s_nop 0
	v_pk_mul_f32 v[186:187], v[64:65], v[172:173] op_sel_hi:[1,0]
	v_pk_mul_f32 v[184:185], v[62:63], v[172:173] op_sel_hi:[1,0]
	v_pk_mul_f32 v[172:173], v[58:59], v[172:173] op_sel_hi:[1,0]
	v_cvt_pk_bf16_f32 v184, v184, v185
	v_cvt_pk_bf16_f32 v185, v186, v187
	s_nop 0
	v_cvt_pk_bf16_f32 v186, v172, v173
	v_cvt_pk_bf16_f32 v187, v190, v191
	s_cmp_lg_u64 s[4:5], 0
	s_cbranch_scc1 .Lwt_13
	global_store_dwordx4 v[188:189], v[184:187], off offset:-3840
.Lwb_13:
	ds_read_b32 v172, v156 offset:320
	v_mul_lo_u32 v173, s18, v162
	v_mad_u64_u32 v[184:185], s[0:1], s18, v160, 0
	v_add3_u32 v185, v185, v173, v161
	v_lshl_add_u64 v[184:185], v[184:185], 1, s[20:21]
	v_lshl_add_u64 v[188:189], v[184:185], 0, v[150:151]
	s_waitcnt lgkmcnt(0)
	v_pk_mul_f32 v[186:187], v[56:57], v[172:173] op_sel_hi:[1,0]
	v_pk_mul_f32 v[184:185], v[54:55], v[172:173] op_sel_hi:[1,0]
	v_pk_mul_f32 v[190:191], v[52:53], v[172:173] op_sel_hi:[1,0]
	v_pk_mul_f32 v[192:193], v[50:51], v[172:173] op_sel_hi:[1,0]
	v_cvt_pk_bf16_f32 v184, v184, v185
	v_cvt_pk_bf16_f32 v185, v186, v187
	s_nop 0
	v_cvt_pk_bf16_f32 v186, v192, v193
	v_cvt_pk_bf16_f32 v187, v190, v191
	s_cmp_lg_u64 s[4:5], 0
	s_cbranch_scc1 .Lwt_14
	global_store_dwordx4 v[188:189], v[184:187], off offset:-4096
.Lwb_14:
	v_pk_mul_f32 v[190:191], v[44:45], v[172:173] op_sel_hi:[1,0]
	s_nop 0
	v_pk_mul_f32 v[186:187], v[48:49], v[172:173] op_sel_hi:[1,0]
	v_pk_mul_f32 v[184:185], v[46:47], v[172:173] op_sel_hi:[1,0]
	v_pk_mul_f32 v[172:173], v[42:43], v[172:173] op_sel_hi:[1,0]
	v_cvt_pk_bf16_f32 v184, v184, v185
	v_cvt_pk_bf16_f32 v185, v186, v187
	s_nop 0
	v_cvt_pk_bf16_f32 v186, v172, v173
	v_cvt_pk_bf16_f32 v187, v190, v191
	s_cmp_lg_u64 s[4:5], 0
	s_cbranch_scc1 .Lwt_15
	global_store_dwordx4 v[188:189], v[184:187], off offset:-3840
.Lwb_15:
	ds_read_b32 v172, v156 offset:384
	v_mul_lo_u32 v173, s18, v159
	v_mad_u64_u32 v[184:185], s[0:1], s18, v157, 0
	v_add3_u32 v185, v185, v173, v158
	v_lshl_add_u64 v[184:185], v[184:185], 1, s[20:21]
	v_lshl_add_u64 v[188:189], v[184:185], 0, v[150:151]
	s_waitcnt lgkmcnt(0)
	v_pk_mul_f32 v[186:187], v[40:41], v[172:173] op_sel_hi:[1,0]
	v_pk_mul_f32 v[184:185], v[38:39], v[172:173] op_sel_hi:[1,0]
	v_pk_mul_f32 v[190:191], v[36:37], v[172:173] op_sel_hi:[1,0]
	v_pk_mul_f32 v[192:193], v[34:35], v[172:173] op_sel_hi:[1,0]
	v_cvt_pk_bf16_f32 v184, v184, v185
	v_cvt_pk_bf16_f32 v185, v186, v187
	s_nop 0
	v_cvt_pk_bf16_f32 v186, v192, v193
	v_cvt_pk_bf16_f32 v187, v190, v191
	s_cmp_lg_u64 s[4:5], 0
	s_cbranch_scc1 .Lwt_16
	global_store_dwordx4 v[188:189], v[184:187], off offset:-4096
.Lwb_16:
	v_pk_mul_f32 v[190:191], v[28:29], v[172:173] op_sel_hi:[1,0]
	s_nop 0
	v_pk_mul_f32 v[186:187], v[32:33], v[172:173] op_sel_hi:[1,0]
	v_pk_mul_f32 v[184:185], v[30:31], v[172:173] op_sel_hi:[1,0]
	v_pk_mul_f32 v[172:173], v[26:27], v[172:173] op_sel_hi:[1,0]
	v_cvt_pk_bf16_f32 v184, v184, v185
	v_cvt_pk_bf16_f32 v185, v186, v187
	s_nop 0
	v_cvt_pk_bf16_f32 v186, v172, v173
	v_cvt_pk_bf16_f32 v187, v190, v191
	s_cmp_lg_u64 s[4:5], 0
	s_cbranch_scc1 .Lwt_17
	global_store_dwordx4 v[188:189], v[184:187], off offset:-3840
.Lwb_17:
	ds_read_b32 v172, v156 offset:448
	v_ashrrev_i32_e32 v173, 31, v155
	v_mul_lo_u32 v173, s18, v173
	v_mad_u64_u32 v[184:185], s[0:1], s18, v155, 0
	v_add3_u32 v185, v185, v173, v183
	v_lshl_add_u64 v[184:185], v[184:185], 1, s[20:21]
	v_lshl_add_u64 v[150:151], v[184:185], 0, v[150:151]
	s_waitcnt lgkmcnt(0)
	v_pk_mul_f32 v[186:187], v[24:25], v[172:173] op_sel_hi:[1,0]
	v_pk_mul_f32 v[184:185], v[22:23], v[172:173] op_sel_hi:[1,0]
	v_pk_mul_f32 v[188:189], v[20:21], v[172:173] op_sel_hi:[1,0]
	v_pk_mul_f32 v[190:191], v[18:19], v[172:173] op_sel_hi:[1,0]
	v_cvt_pk_bf16_f32 v184, v184, v185
	v_cvt_pk_bf16_f32 v185, v186, v187
	s_nop 0
	v_cvt_pk_bf16_f32 v186, v190, v191
	v_cvt_pk_bf16_f32 v187, v188, v189
	s_cmp_lg_u64 s[4:5], 0
	s_cbranch_scc1 .Lwt_18
	global_store_dwordx4 v[150:151], v[184:187], off offset:-4096
.Lwb_18:
	v_pk_mul_f32 v[188:189], v[12:13], v[172:173] op_sel_hi:[1,0]
	s_nop 0
	v_pk_mul_f32 v[186:187], v[16:17], v[172:173] op_sel_hi:[1,0]
	v_pk_mul_f32 v[184:185], v[14:15], v[172:173] op_sel_hi:[1,0]
	v_pk_mul_f32 v[172:173], v[10:11], v[172:173] op_sel_hi:[1,0]
	v_cvt_pk_bf16_f32 v184, v184, v185
	v_cvt_pk_bf16_f32 v185, v186, v187
	s_nop 0
	v_cvt_pk_bf16_f32 v186, v172, v173
	v_cvt_pk_bf16_f32 v187, v188, v189
	s_cmp_lg_u64 s[4:5], 0
	s_cbranch_scc1 .Lwt_19
	global_store_dwordx4 v[150:151], v[184:187], off offset:-3840
.Lwb_19:
	s_cbranch_execz .LBB0_308

; __device__ __forceinline__ unsigned pk2(float lo, float hi) { unsigned r; asm volatile("v_cvt_pk_bf16_f32 %0, %1, %2" : "=v"(r) : "v"(lo), "v"(hi)); return r; }
;     __device__ __forceinline__ void fast(const f32x4 (&acc)[2][2][4][2], const pg8::Unit& u, int wr, int wc, int fr, int fq, RsCache& rsc) const {
;     ...
;         if (u.pn < 8) {
;             const int cb = 1024 + u.pn * 128 + wc * 32 + 8 * fq;
; #pragma unroll
;             for (int ai = 0; ai < 2; ++ai)
; #pragma unroll
;                 for (int m = 0; m < 4; ++m) { const int row = row0 + ai * 128 + m * 16; const float s = rsc.tab[ai * 64 + m * 16 + fr]; const float s2 = s * s;
;                     const f32x4 v0 = acc[ai][0][m][0] * acc[ai][1][m][0] * s2, v1 = acc[ai][0][m][1] * acc[ai][1][m][1] * s2;
;                     u32x4 w; w.x = pk2(v0[0], v0[1]); w.y = pk2(v0[2], v0[3]); w.z = pk2(v1[0], v1[1]); w.w = pk2(v1[2], v1[3]);
;                     *(u32x4*)(out + (size_t)row * ldc + cb) = w;
;                     asm volatile("" ::: "memory"); }
.LBB0_308:
	s_waitcnt lgkmcnt(0)
	v_mul_f32_e32 v148, v148, v148
	v_pk_mul_f32 v[126:127], v[134:135], v[126:127]
	v_pk_mul_f32 v[122:123], v[130:131], v[122:123]
	s_lshl_b32 s0, s3, 7
	v_pk_mul_f32 v[128:129], v[136:137], v[128:129]
	v_pk_mul_f32 v[126:127], v[126:127], v[148:149] op_sel_hi:[1,0]
	v_pk_mul_f32 v[124:125], v[132:133], v[124:125]
	v_pk_mul_f32 v[122:123], v[122:123], v[148:149] op_sel_hi:[1,0]
	v_pk_mul_f32 v[128:129], v[128:129], v[148:149] op_sel_hi:[1,0]
	v_pk_mul_f32 v[130:131], v[124:125], v[148:149] op_sel_hi:[1,0]
	v_cvt_pk_bf16_f32 v124, v126, v127
	v_cvt_pk_bf16_f32 v125, v128, v129
	v_cvt_pk_bf16_f32 v126, v122, v123
	v_mad_u64_u32 v[122:123], s[80:81], s18, v180, 0
	s_ashr_i32 s1, s0, 31
	v_add3_u32 v123, v123, v182, v181
	s_or_b64 s[0:1], s[8:9], s[0:1]
	v_lshl_add_u64 v[128:129], v[122:123], 1, s[20:21]
	v_lshl_add_u64 v[122:123], s[0:1], 0, v[146:147]
	v_lshlrev_b64 v[122:123], 1, v[122:123]
	v_lshl_add_u64 v[128:129], v[128:129], 0, v[122:123]
	v_cvt_pk_bf16_f32 v127, v130, v131
	s_cmp_lg_u64 s[4:5], 0
	s_cbranch_scc1 .Lwt_20
	global_store_dwordx4 v[128:129], v[124:127], off offset:2048
.Lwb_20:
	ds_read_b32 v124, v156 offset:64
	v_pk_mul_f32 v[112:113], v[120:121], v[112:113]
	v_pk_mul_f32 v[110:111], v[118:119], v[110:111]
	v_pk_mul_f32 v[108:109], v[116:117], v[108:109]
	v_pk_mul_f32 v[106:107], v[114:115], v[106:107]
	s_waitcnt lgkmcnt(0)
	v_mul_f32_e32 v124, v124, v124
	v_pk_mul_f32 v[112:113], v[112:113], v[124:125] op_sel_hi:[1,0]
	v_pk_mul_f32 v[110:111], v[110:111], v[124:125] op_sel_hi:[1,0]
	v_pk_mul_f32 v[114:115], v[108:109], v[124:125] op_sel_hi:[1,0]
	v_pk_mul_f32 v[108:109], v[106:107], v[124:125] op_sel_hi:[1,0]
	v_cvt_pk_bf16_f32 v106, v110, v111
	v_cvt_pk_bf16_f32 v107, v112, v113
	v_mul_lo_u32 v112, s18, v179
	v_mad_u64_u32 v[110:111], s[0:1], s18, v177, 0
	v_add3_u32 v111, v111, v112, v178
	v_lshl_add_u64 v[110:111], v[110:111], 1, s[20:21]
	v_lshl_add_u64 v[110:111], v[110:111], 0, v[122:123]
	v_cvt_pk_bf16_f32 v108, v108, v109
	v_cvt_pk_bf16_f32 v109, v114, v115
	s_cmp_lg_u64 s[4:5], 0
	s_cbranch_scc1 .Lwt_21
	global_store_dwordx4 v[110:111], v[106:109], off offset:2048
.Lwb_21:
	ds_read_b32 v106, v156 offset:128
	v_pk_mul_f32 v[96:97], v[104:105], v[96:97]
	v_pk_mul_f32 v[94:95], v[102:103], v[94:95]
	v_pk_mul_f32 v[92:93], v[100:101], v[92:93]
	v_pk_mul_f32 v[90:91], v[98:99], v[90:91]
	s_waitcnt lgkmcnt(0)
	v_mul_f32_e32 v106, v106, v106
	v_pk_mul_f32 v[96:97], v[96:97], v[106:107] op_sel_hi:[1,0]
	v_pk_mul_f32 v[94:95], v[94:95], v[106:107] op_sel_hi:[1,0]
	v_pk_mul_f32 v[98:99], v[92:93], v[106:107] op_sel_hi:[1,0]
	v_pk_mul_f32 v[92:93], v[90:91], v[106:107] op_sel_hi:[1,0]
	v_cvt_pk_bf16_f32 v90, v94, v95
	v_cvt_pk_bf16_f32 v91, v96, v97
	v_mul_lo_u32 v96, s18, v176
	v_mad_u64_u32 v[94:95], s[0:1], s18, v169, 0
	v_add3_u32 v95, v95, v96, v175
	v_lshl_add_u64 v[94:95], v[94:95], 1, s[20:21]
	v_lshl_add_u64 v[94:95], v[94:95], 0, v[122:123]
	v_cvt_pk_bf16_f32 v92, v92, v93
	v_cvt_pk_bf16_f32 v93, v98, v99
	s_cmp_lg_u64 s[4:5], 0
	s_cbranch_scc1 .Lwt_22
	global_store_dwordx4 v[94:95], v[90:93], off offset:2048
.Lwb_22:
	ds_read_b32 v90, v156 offset:192
	v_pk_mul_f32 v[80:81], v[88:89], v[80:81]
	v_pk_mul_f32 v[78:79], v[86:87], v[78:79]
	v_pk_mul_f32 v[76:77], v[84:85], v[76:77]
	v_pk_mul_f32 v[74:75], v[82:83], v[74:75]
	s_waitcnt lgkmcnt(0)
	v_mul_f32_e32 v90, v90, v90
	v_pk_mul_f32 v[80:81], v[80:81], v[90:91] op_sel_hi:[1,0]
	v_pk_mul_f32 v[78:79], v[78:79], v[90:91] op_sel_hi:[1,0]
	v_pk_mul_f32 v[82:83], v[76:77], v[90:91] op_sel_hi:[1,0]
	v_pk_mul_f32 v[76:77], v[74:75], v[90:91] op_sel_hi:[1,0]
	v_cvt_pk_bf16_f32 v74, v78, v79
	v_cvt_pk_bf16_f32 v75, v80, v81
	v_mul_lo_u32 v80, s18, v168
	v_mad_u64_u32 v[78:79], s[0:1], s18, v166, 0
	v_add3_u32 v79, v79, v80, v167
	v_lshl_add_u64 v[78:79], v[78:79], 1, s[20:21]
	v_lshl_add_u64 v[78:79], v[78:79], 0, v[122:123]
	v_cvt_pk_bf16_f32 v76, v76, v77
	v_cvt_pk_bf16_f32 v77, v82, v83
	s_cmp_lg_u64 s[4:5], 0
	s_cbranch_scc1 .Lwt_23
	global_store_dwordx4 v[78:79], v[74:77], off offset:2048
; __device__ __forceinline__ unsigned pk2(float lo, float hi) { unsigned r; asm volatile("v_cvt_pk_bf16_f32 %0, %1, %2" : "=v"(r) : "v"(lo), "v"(hi)); return r; }
;     __device__ __forceinline__ void fast(const f32x4 (&acc)[2][2][4][2], const pg8::Unit& u, int wr, int wc, int fr, int fq, RsCache& rsc) const {
;     ...
;         if (u.pn < 8) {
;             const int cb = 1024 + u.pn * 128 + wc * 32 + 8 * fq;
; #pragma unroll
;             for (int ai = 0; ai < 2; ++ai)
; #pragma unroll
;                 for (int m = 0; m < 4; ++m) { const int row = row0 + ai * 128 + m * 16; const float s = rsc.tab[ai * 64 + m * 16 + fr]; const float s2 = s * s;
;                     const f32x4 v0 = acc[ai][0][m][0] * acc[ai][1][m][0] * s2, v1 = acc[ai][0][m][1] * acc[ai][1][m][1] * s2;
;                     u32x4 w; w.x = pk2(v0[0], v0[1]); w.y = pk2(v0[2], v0[3]); w.z = pk2(v1[0], v1[1]); w.w = pk2(v1[2], v1[3]);
;                     *(u32x4*)(out + (size_t)row * ldc + cb) = w;
;                     asm volatile("" ::: "memory"); }
.Lwb_23:
	ds_read_b32 v74, v156 offset:256
	v_pk_mul_f32 v[64:65], v[72:73], v[64:65]
	v_pk_mul_f32 v[62:63], v[70:71], v[62:63]
	v_pk_mul_f32 v[60:61], v[68:69], v[60:61]
	v_pk_mul_f32 v[58:59], v[66:67], v[58:59]
	s_waitcnt lgkmcnt(0)
	v_mul_f32_e32 v74, v74, v74
	v_pk_mul_f32 v[64:65], v[64:65], v[74:75] op_sel_hi:[1,0]
	v_pk_mul_f32 v[62:63], v[62:63], v[74:75] op_sel_hi:[1,0]
	v_pk_mul_f32 v[66:67], v[60:61], v[74:75] op_sel_hi:[1,0]
	v_pk_mul_f32 v[60:61], v[58:59], v[74:75] op_sel_hi:[1,0]
	v_cvt_pk_bf16_f32 v58, v62, v63
	v_cvt_pk_bf16_f32 v59, v64, v65
	v_mul_lo_u32 v64, s18, v165
	v_mad_u64_u32 v[62:63], s[0:1], s18, v163, 0
	v_add3_u32 v63, v63, v64, v164
	v_lshl_add_u64 v[62:63], v[62:63], 1, s[20:21]
	v_lshl_add_u64 v[62:63], v[62:63], 0, v[122:123]
	v_cvt_pk_bf16_f32 v60, v60, v61
	v_cvt_pk_bf16_f32 v61, v66, v67
	s_cmp_lg_u64 s[4:5], 0
	s_cbranch_scc1 .Lwt_24
	global_store_dwordx4 v[62:63], v[58:61], off offset:2048
.Lwb_24:
	ds_read_b32 v58, v156 offset:320
	v_pk_mul_f32 v[48:49], v[56:57], v[48:49]
	v_pk_mul_f32 v[46:47], v[54:55], v[46:47]
	v_pk_mul_f32 v[44:45], v[52:53], v[44:45]
	v_pk_mul_f32 v[42:43], v[50:51], v[42:43]
	s_waitcnt lgkmcnt(0)
	v_mul_f32_e32 v58, v58, v58
	v_pk_mul_f32 v[48:49], v[48:49], v[58:59] op_sel_hi:[1,0]
	v_pk_mul_f32 v[46:47], v[46:47], v[58:59] op_sel_hi:[1,0]
	v_pk_mul_f32 v[50:51], v[44:45], v[58:59] op_sel_hi:[1,0]
	v_pk_mul_f32 v[44:45], v[42:43], v[58:59] op_sel_hi:[1,0]
	v_cvt_pk_bf16_f32 v42, v46, v47
	v_cvt_pk_bf16_f32 v43, v48, v49
	v_mul_lo_u32 v48, s18, v162
	v_mad_u64_u32 v[46:47], s[0:1], s18, v160, 0
	v_add3_u32 v47, v47, v48, v161
	v_lshl_add_u64 v[46:47], v[46:47], 1, s[20:21]
	v_lshl_add_u64 v[46:47], v[46:47], 0, v[122:123]
	v_cvt_pk_bf16_f32 v44, v44, v45
	v_cvt_pk_bf16_f32 v45, v50, v51
	s_cmp_lg_u64 s[4:5], 0
	s_cbranch_scc1 .Lwt_25
	global_store_dwordx4 v[46:47], v[42:45], off offset:2048
.Lwb_25:
	ds_read_b32 v42, v156 offset:384
	v_pk_mul_f32 v[32:33], v[40:41], v[32:33]
	v_pk_mul_f32 v[30:31], v[38:39], v[30:31]
	v_pk_mul_f32 v[28:29], v[36:37], v[28:29]
	v_pk_mul_f32 v[26:27], v[34:35], v[26:27]
	s_waitcnt lgkmcnt(0)
	v_mul_f32_e32 v42, v42, v42
	v_pk_mul_f32 v[32:33], v[32:33], v[42:43] op_sel_hi:[1,0]
	v_pk_mul_f32 v[30:31], v[30:31], v[42:43] op_sel_hi:[1,0]
	v_pk_mul_f32 v[34:35], v[28:29], v[42:43] op_sel_hi:[1,0]
	v_pk_mul_f32 v[28:29], v[26:27], v[42:43] op_sel_hi:[1,0]
	v_cvt_pk_bf16_f32 v26, v30, v31
	v_cvt_pk_bf16_f32 v27, v32, v33
	v_mul_lo_u32 v32, s18, v159
	v_mad_u64_u32 v[30:31], s[0:1], s18, v157, 0
	v_add3_u32 v31, v31, v32, v158
	v_lshl_add_u64 v[30:31], v[30:31], 1, s[20:21]
	v_lshl_add_u64 v[30:31], v[30:31], 0, v[122:123]
	v_cvt_pk_bf16_f32 v28, v28, v29
	v_cvt_pk_bf16_f32 v29, v34, v35
	s_cmp_lg_u64 s[4:5], 0
	s_cbranch_scc1 .Lwt_26
	global_store_dwordx4 v[30:31], v[26:29], off offset:2048
.Lwb_26:
	ds_read_b32 v26, v156 offset:448
	v_pk_mul_f32 v[14:15], v[22:23], v[14:15]
	v_pk_mul_f32 v[16:17], v[24:25], v[16:17]
	v_pk_mul_f32 v[12:13], v[20:21], v[12:13]
	v_pk_mul_f32 v[10:11], v[18:19], v[10:11]
	s_waitcnt lgkmcnt(0)
	v_mul_f32_e32 v26, v26, v26
	v_pk_mul_f32 v[14:15], v[14:15], v[26:27] op_sel_hi:[1,0]
	v_pk_mul_f32 v[16:17], v[16:17], v[26:27] op_sel_hi:[1,0]
	v_pk_mul_f32 v[18:19], v[12:13], v[26:27] op_sel_hi:[1,0]
	v_pk_mul_f32 v[12:13], v[10:11], v[26:27] op_sel_hi:[1,0]
	v_cvt_pk_bf16_f32 v10, v14, v15
	v_ashrrev_i32_e32 v14, 31, v155
	v_cvt_pk_bf16_f32 v11, v16, v17
	v_mul_lo_u32 v16, s18, v14
	v_mul_lo_u32 v17, s19, v155
	v_mad_u64_u32 v[14:15], s[0:1], s18, v155, 0
	v_add3_u32 v15, v15, v16, v17
	v_lshl_add_u64 v[14:15], v[14:15], 1, s[20:21]
	v_lshl_add_u64 v[14:15], v[14:15], 0, v[122:123]
	v_cvt_pk_bf16_f32 v12, v12, v13
	v_cvt_pk_bf16_f32 v13, v18, v19
	s_cmp_lg_u64 s[4:5], 0
	s_cbranch_scc1 .Lwt_27
	global_store_dwordx4 v[14:15], v[10:13], off offset:2048
.Lwb_27:
	s_and_b64 vcc, exec, s[4:5]
	s_mov_b64 s[0:1], -1
	s_cbranch_vccnz .LBB0_289
.LBB0_309:
	s_andn2_b64 vcc, exec, s[6:7]
	s_cbranch_vccnz .LBB0_288
	s_barrier
	s_branch .LBB0_288
.Lwt_4:
	global_store_dwordx4 v[172:173], v[184:187], off offset:-4096 sc1
	s_branch .Lwb_4
.Lwt_5:
	global_store_dwordx4 v[172:173], v[184:187], off offset:-3840 sc1
	s_branch .Lwb_5
.Lwt_6:
	global_store_dwordx4 v[188:189], v[184:187], off offset:-4096 sc1
	s_branch .Lwb_6
.Lwt_7:
	global_store_dwordx4 v[188:189], v[184:187], off offset:-3840 sc1
	s_branch .Lwb_7

; __device__ __forceinline__ unsigned pk2(float lo, float hi) { unsigned r; asm volatile("v_cvt_pk_bf16_f32 %0, %1, %2" : "=v"(r) : "v"(lo), "v"(hi)); return r; }
;     __device__ __forceinline__ void fast(const f32x4 (&acc)[2][2][4][2], const pg8::Unit& u, int wr, int wc, int fr, int fq, RsCache& rsc) const {
;     ...
;             const int cb = 1024 + u.pn * 128 + wc * 32 + 8 * fq;
; #pragma unroll
;             for (int ai = 0; ai < 2; ++ai)
; #pragma unroll
;                 for (int m = 0; m < 4; ++m) { const int row = row0 + ai * 128 + m * 16; const float s = rsc.tab[ai * 64 + m * 16 + fr]; const float s2 = s * s;
;                     const f32x4 v0 = acc[ai][0][m][0] * acc[ai][1][m][0] * s2, v1 = acc[ai][0][m][1] * acc[ai][1][m][1] * s2;
;                     u32x4 w; w.x = pk2(v0[0], v0[1]); w.y = pk2(v0[2], v0[3]); w.z = pk2(v1[0], v1[1]); w.w = pk2(v1[2], v1[3]);
;                     *(u32x4*)(out + (size_t)row * ldc + cb) = w;
;                     asm volatile("" ::: "memory"); }
;         } else {
;             const int cb = (u.pn - 8) * 256 + wc * 32 + 8 * fq;
; #pragma unroll
;             for (int ai = 0; ai < 2; ++ai)
; #pragma unroll
;                 for (int m = 0; m < 4; ++m) { const int row = row0 + ai * 128 + m * 16; const float s = rsc.tab[ai * 64 + m * 16 + fr]; bf16_t* rowp = out + (size_t)row * ldc + cb;
; #pragma unroll
;                     for (int bj = 0; bj < 2; ++bj) { const f32x4 v0 = acc[ai][bj][m][0] * s, v1 = acc[ai][bj][m][1] * s;
;                         u32x4 w; w.x = pk2(v0[0], v0[1]); w.y = pk2(v0[2], v0[3]); w.z = pk2(v1[0], v1[1]); w.w = pk2(v1[2], v1[3]);
;                         *(u32x4*)(rowp + bj * 128) = w; }
.Lwt_18:
	global_store_dwordx4 v[150:151], v[184:187], off offset:-4096 sc1
	s_branch .Lwb_18
.Lwt_19:
	global_store_dwordx4 v[150:151], v[184:187], off offset:-3840 sc1
	s_branch .Lwb_19
.Lwt_20:
	global_store_dwordx4 v[128:129], v[124:127], off offset:2048 sc1
	s_branch .Lwb_20
.Lwt_21:
	global_store_dwordx4 v[110:111], v[106:109], off offset:2048 sc1
	s_branch .Lwb_21
.Lwt_22:
	global_store_dwordx4 v[94:95], v[90:93], off offset:2048 sc1
	s_branch .Lwb_22
.Lwt_23:
	global_store_dwordx4 v[78:79], v[74:77], off offset:2048 sc1
	s_branch .Lwb_23
.Lwt_24:
	global_store_dwordx4 v[62:63], v[58:61], off offset:2048 sc1
	s_branch .Lwb_24
.Lwt_25:
	global_store_dwordx4 v[46:47], v[42:45], off offset:2048 sc1
	s_branch .Lwb_25
.Lwt_26:
	global_store_dwordx4 v[30:31], v[26:29], off offset:2048 sc1
	s_branch .Lwb_26
.Lwt_27:
	global_store_dwordx4 v[14:15], v[10:13], off offset:2048 sc1
	s_branch .Lwb_27

; __device__ __forceinline__ unsigned pk2(float lo, float hi) { unsigned r; asm volatile("v_cvt_pk_bf16_f32 %0, %1, %2" : "=v"(r) : "v"(lo), "v"(hi)); return r; }
;     __device__ __forceinline__ void fast(const f32x4 (&acc)[2][2][4][2], const pg8::Unit& u, int wr, int wc, int fr, int fq, RsCache& rsc) const {
;         asm volatile("" : "+v"(fr), "+v"(fq));
;         rs_cache_fill(rsc, rs, u.pm, wr, fq * 16 + fr);
;         const int row0 = u.pm * 256 + wr * 64 + fr;
;         if (u.pn < 24) {
;             const int cb = u.pn * 256 + wc * 32 + 8 * fq; const bool hal = (u.pn >= 8) && (fr >= 13);
; #pragma unroll
;             for (int ai = 0; ai < 2; ++ai)
; #pragma unroll
;                 for (int m = 0; m < 4; ++m) { const int row = row0 + ai * 128 + m * 16; const float s = rsc.tab[ai * 64 + m * 16 + fr]; bf16_t* rowp = big + (size_t)row * BIGW + cb;
; #pragma unroll
;                     for (int bj = 0; bj < 2; ++bj) { const f32x4 v0 = acc[ai][bj][m][0] * s, v1 = acc[ai][bj][m][1] * s;
;                         u32x4 w; w.x = pk2(v0[0], v0[1]); w.y = pk2(v0[2], v0[3]); w.z = pk2(v1[0], v1[1]); w.w = pk2(v1[2], v1[3]);
;                         *(u32x4*)(rowp + bj * 128) = w;
;                         if (m == 3 && hal) *(u32x4*)(halo + ((size_t)(row >> 6) * 3 + (fr - 13)) * 4096 + (cb - DI_) + bj * 128) = w; }
;                     asm volatile("" ::: "memory"); }
.LBB0_340:
	v_lshl_add_u32 v142, v177, 2, s8
	s_lshl_b32 s0, s21, 8
	ds_read_b32 v144, v142
	s_or_b32 s0, s0, s97
	v_readlane_b32 s2, v253, 16
	v_lshl_add_u32 v138, v2, 3, s0
	v_readlane_b32 s3, v253, 17
	v_ashrrev_i32_e32 v139, 31, v138
	s_movk_i32 s10, 0x3000
	v_mov_b64_e32 v[146:147], s[2:3]
	v_mad_i64_i32 v[148:149], s[2:3], v164, s10, v[146:147]
	v_lshlrev_b64 v[140:141], 1, v[138:139]
	v_lshl_add_u64 v[148:149], v[148:149], 0, v[140:141]
	s_waitcnt lgkmcnt(0)
	v_pk_mul_f32 v[136:137], v[136:137], v[144:145] op_sel_hi:[1,0]
	v_pk_mul_f32 v[134:135], v[134:135], v[144:145] op_sel_hi:[1,0]
	v_pk_mul_f32 v[150:151], v[132:133], v[144:145] op_sel_hi:[1,0]
	v_pk_mul_f32 v[132:133], v[130:131], v[144:145] op_sel_hi:[1,0]
	v_cvt_pk_bf16_f32 v130, v134, v135
	v_cvt_pk_bf16_f32 v131, v136, v137
	v_pk_mul_f32 v[128:129], v[128:129], v[144:145] op_sel_hi:[1,0]
	v_cvt_pk_bf16_f32 v132, v132, v133
	v_cvt_pk_bf16_f32 v133, v150, v151
	s_cmp_lg_u64 s[4:5], 0
	s_cbranch_scc1 .Lwt_28
	global_store_dwordx4 v[148:149], v[130:133], off
.Lwb_28:
	v_pk_mul_f32 v[126:127], v[126:127], v[144:145] op_sel_hi:[1,0]
	v_add_u32_e32 v2, -13, v177
	v_pk_mul_f32 v[130:131], v[120:121], v[144:145] op_sel_hi:[1,0]
	v_pk_mul_f32 v[120:121], v[118:119], v[144:145] op_sel_hi:[1,0]
	v_cvt_pk_bf16_f32 v118, v126, v127
	v_cvt_pk_bf16_f32 v119, v128, v129
	v_cvt_pk_bf16_f32 v120, v120, v121
	v_cvt_pk_bf16_f32 v121, v130, v131
	s_cmp_lg_u64 s[4:5], 0
	s_cbranch_scc1 .Lwt_29
	global_store_dwordx4 v[148:149], v[118:121], off offset:256
.Lwb_29:
	ds_read_b32 v118, v142 offset:64
	s_cmp_gt_i32 s21, 7
	s_cselect_b64 s[0:1], -1, 0
	v_add_u32_e32 v119, 16, v164
	v_mad_i64_i32 v[120:121], s[2:3], v119, s10, v[146:147]
	v_lshl_add_u64 v[120:121], v[120:121], 0, v[140:141]
	s_waitcnt lgkmcnt(0)
	v_pk_mul_f32 v[124:125], v[124:125], v[118:119] op_sel_hi:[1,0]
	v_pk_mul_f32 v[122:123], v[122:123], v[118:119] op_sel_hi:[1,0]
	v_pk_mul_f32 v[126:127], v[116:117], v[118:119] op_sel_hi:[1,0]
	v_pk_mul_f32 v[116:117], v[114:115], v[118:119] op_sel_hi:[1,0]
	v_cvt_pk_bf16_f32 v114, v122, v123
	v_cvt_pk_bf16_f32 v115, v124, v125
	v_pk_mul_f32 v[112:113], v[112:113], v[118:119] op_sel_hi:[1,0]
	v_cvt_pk_bf16_f32 v116, v116, v117
	v_cvt_pk_bf16_f32 v117, v126, v127
	s_cmp_lg_u64 s[4:5], 0
	s_cbranch_scc1 .Lwt_30
	global_store_dwordx4 v[120:121], v[114:117], off
.Lwb_30:
	v_pk_mul_f32 v[110:111], v[110:111], v[118:119] op_sel_hi:[1,0]
	v_cmp_lt_i32_e32 vcc, 12, v177
	v_pk_mul_f32 v[114:115], v[104:105], v[118:119] op_sel_hi:[1,0]
	v_pk_mul_f32 v[104:105], v[102:103], v[118:119] op_sel_hi:[1,0]
	v_cvt_pk_bf16_f32 v102, v110, v111
	v_cvt_pk_bf16_f32 v103, v112, v113
	s_and_b64 s[0:1], s[0:1], vcc
	v_cvt_pk_bf16_f32 v104, v104, v105
	v_cvt_pk_bf16_f32 v105, v114, v115
	s_cmp_lg_u64 s[4:5], 0
	s_cbranch_scc1 .Lwt_31
	global_store_dwordx4 v[120:121], v[102:105], off offset:256
.Lwb_31:
	ds_read_b32 v102, v142 offset:128
	s_nop 0
	v_add_u32_e32 v103, 32, v164
	v_mad_i64_i32 v[104:105], s[2:3], v103, s10, v[146:147]
	v_lshl_add_u64 v[104:105], v[104:105], 0, v[140:141]
	s_waitcnt lgkmcnt(0)
	v_pk_mul_f32 v[108:109], v[108:109], v[102:103] op_sel_hi:[1,0]
	v_pk_mul_f32 v[106:107], v[106:107], v[102:103] op_sel_hi:[1,0]
	v_pk_mul_f32 v[110:111], v[100:101], v[102:103] op_sel_hi:[1,0]
	v_pk_mul_f32 v[100:101], v[98:99], v[102:103] op_sel_hi:[1,0]
	v_cvt_pk_bf16_f32 v98, v106, v107
	v_cvt_pk_bf16_f32 v99, v108, v109
	v_pk_mul_f32 v[96:97], v[96:97], v[102:103] op_sel_hi:[1,0]
	v_cvt_pk_bf16_f32 v100, v100, v101
	v_cvt_pk_bf16_f32 v101, v110, v111
	s_cmp_lg_u64 s[4:5], 0
	s_cbranch_scc1 .Lwt_32
	global_store_dwordx4 v[104:105], v[98:101], off
.Lwb_32:
	v_pk_mul_f32 v[94:95], v[94:95], v[102:103] op_sel_hi:[1,0]
	s_nop 0
	v_pk_mul_f32 v[98:99], v[92:93], v[102:103] op_sel_hi:[1,0]
	v_pk_mul_f32 v[92:93], v[90:91], v[102:103] op_sel_hi:[1,0]
	v_cvt_pk_bf16_f32 v90, v94, v95
	v_cvt_pk_bf16_f32 v91, v96, v97
	s_nop 0
	v_cvt_pk_bf16_f32 v92, v92, v93
	v_cvt_pk_bf16_f32 v93, v98, v99
	s_cmp_lg_u64 s[4:5], 0
	s_cbranch_scc1 .Lwt_33
	global_store_dwordx4 v[104:105], v[90:93], off offset:256
.Lwb_33:
	ds_read_b32 v92, v142 offset:192
	s_nop 0
	v_add_u32_e32 v93, 48, v164
	v_mad_i64_i32 v[90:91], s[2:3], v93, s10, v[146:147]
	v_ashrrev_i32_e32 v93, 6, v93
	v_lshl_add_u32 v94, v93, 1, v93
	v_ashrrev_i32_e32 v95, 31, v94
	v_lshl_add_u64 v[94:95], v[94:95], 0, v[2:3]
	v_readlane_b32 s2, v254, 1
	v_lshlrev_b64 v[94:95], 13, v[94:95]
	s_waitcnt lgkmcnt(0)
	v_pk_mul_f32 v[86:87], v[86:87], v[92:93] op_sel_hi:[1,0]
	v_readlane_b32 s3, v254, 2
	v_pk_mul_f32 v[96:97], v[84:85], v[92:93] op_sel_hi:[1,0]
	v_pk_mul_f32 v[84:85], v[82:83], v[92:93] op_sel_hi:[1,0]
	v_cvt_pk_bf16_f32 v82, v86, v87
	v_lshl_add_u64 v[86:87], s[2:3], 0, v[94:95]
	v_lshl_add_u64 v[90:91], v[90:91], 0, v[140:141]
	v_lshl_add_u64 v[86:87], v[138:139], 1, v[86:87]
	v_pk_mul_f32 v[88:89], v[88:89], v[92:93] op_sel_hi:[1,0]
	s_nop 0
	v_cvt_pk_bf16_f32 v83, v88, v89
	v_cvt_pk_bf16_f32 v84, v84, v85
	v_cvt_pk_bf16_f32 v85, v96, v97
	s_cmp_lg_u64 s[4:5], 0
	s_cbranch_scc1 .Lwt_34
	global_store_dwordx4 v[90:91], v[82:85], off
.Lwb_34:
	s_and_saveexec_b64 s[82:83], s[0:1]
	s_cbranch_execz .LBB0_342
	s_cmp_lg_u64 s[4:5], 0
	s_cbranch_scc1 .Lwt_35
	global_store_dwordx4 v[86:87], v[82:85], off offset:-4096
.Lwb_35:
.LBB0_342:
	s_or_b64 exec, exec, s[82:83]
	v_mov_b32_e32 v93, v92
	v_mov_b32_e32 v82, v92
	v_mov_b32_e32 v83, v92
	v_pk_mul_f32 v[80:81], v[80:81], v[82:83]
	v_pk_mul_f32 v[82:83], v[76:77], v[82:83]
	v_pk_mul_f32 v[76:77], v[74:75], v[92:93]
	v_pk_mul_f32 v[78:79], v[78:79], v[92:93]
	s_nop 0
	v_cvt_pk_bf16_f32 v74, v78, v79
	v_cvt_pk_bf16_f32 v75, v80, v81
	v_cvt_pk_bf16_f32 v76, v76, v77
	v_cvt_pk_bf16_f32 v77, v82, v83
	s_cmp_lg_u64 s[4:5], 0
	s_cbranch_scc1 .Lwt_36
	global_store_dwordx4 v[90:91], v[74:77], off offset:256
; __device__ __forceinline__ unsigned pk2(float lo, float hi) { unsigned r; asm volatile("v_cvt_pk_bf16_f32 %0, %1, %2" : "=v"(r) : "v"(lo), "v"(hi)); return r; }
;     __device__ __forceinline__ void fast(const f32x4 (&acc)[2][2][4][2], const pg8::Unit& u, int wr, int wc, int fr, int fq, RsCache& rsc) const {
;     ...
;             for (int ai = 0; ai < 2; ++ai)
; #pragma unroll
;                 for (int m = 0; m < 4; ++m) { const int row = row0 + ai * 128 + m * 16; const float s = rsc.tab[ai * 64 + m * 16 + fr]; bf16_t* rowp = big + (size_t)row * BIGW + cb;
; #pragma unroll
;                     for (int bj = 0; bj < 2; ++bj) { const f32x4 v0 = acc[ai][bj][m][0] * s, v1 = acc[ai][bj][m][1] * s;
;                         u32x4 w; w.x = pk2(v0[0], v0[1]); w.y = pk2(v0[2], v0[3]); w.z = pk2(v1[0], v1[1]); w.w = pk2(v1[2], v1[3]);
;                         *(u32x4*)(rowp + bj * 128) = w;
;                         if (m == 3 && hal) *(u32x4*)(halo + ((size_t)(row >> 6) * 3 + (fr - 13)) * 4096 + (cb - DI_) + bj * 128) = w; }
;                     asm volatile("" ::: "memory"); }
.Lwb_36:
	s_and_saveexec_b64 s[82:83], s[0:1]
	s_cbranch_execz .LBB0_344
	s_cmp_lg_u64 s[4:5], 0
	s_cbranch_scc1 .Lwt_37
	global_store_dwordx4 v[86:87], v[74:77], off offset:-3840
.Lwb_37:
.LBB0_344:
	s_or_b64 exec, exec, s[82:83]
	ds_read_b32 v74, v142 offset:256
	v_readlane_b32 s2, v253, 16
	v_readlane_b32 s3, v253, 17
	v_add_u32_e32 v75, 0x80, v164
	s_waitcnt lgkmcnt(0)
	v_pk_mul_f32 v[72:73], v[72:73], v[74:75] op_sel_hi:[1,0]
	v_mov_b64_e32 v[76:77], s[2:3]
	v_mad_i64_i32 v[78:79], s[2:3], v75, s10, v[76:77]
	v_lshl_add_u64 v[78:79], v[78:79], 0, v[140:141]
	v_pk_mul_f32 v[70:71], v[70:71], v[74:75] op_sel_hi:[1,0]
	v_pk_mul_f32 v[80:81], v[68:69], v[74:75] op_sel_hi:[1,0]
	v_pk_mul_f32 v[68:69], v[66:67], v[74:75] op_sel_hi:[1,0]
	v_cvt_pk_bf16_f32 v66, v70, v71
	v_cvt_pk_bf16_f32 v67, v72, v73
	v_pk_mul_f32 v[64:65], v[64:65], v[74:75] op_sel_hi:[1,0]
	v_cvt_pk_bf16_f32 v68, v68, v69
	v_cvt_pk_bf16_f32 v69, v80, v81
	s_cmp_lg_u64 s[4:5], 0
	s_cbranch_scc1 .Lwt_38
	global_store_dwordx4 v[78:79], v[66:69], off
.Lwb_38:
	v_pk_mul_f32 v[62:63], v[62:63], v[74:75] op_sel_hi:[1,0]
	s_nop 0
	v_pk_mul_f32 v[66:67], v[56:57], v[74:75] op_sel_hi:[1,0]
	v_pk_mul_f32 v[56:57], v[54:55], v[74:75] op_sel_hi:[1,0]
	v_cvt_pk_bf16_f32 v54, v62, v63
	v_cvt_pk_bf16_f32 v55, v64, v65
	s_nop 0
	v_cvt_pk_bf16_f32 v56, v56, v57
	v_cvt_pk_bf16_f32 v57, v66, v67
	s_cmp_lg_u64 s[4:5], 0
	s_cbranch_scc1 .Lwt_39
	global_store_dwordx4 v[78:79], v[54:57], off offset:256
.Lwb_39:
	ds_read_b32 v54, v142 offset:320
	s_nop 0
	v_add_u32_e32 v55, 0x90, v164
	v_mad_i64_i32 v[56:57], s[2:3], v55, s10, v[76:77]
	v_lshl_add_u64 v[56:57], v[56:57], 0, v[140:141]
	s_waitcnt lgkmcnt(0)
	v_pk_mul_f32 v[60:61], v[60:61], v[54:55] op_sel_hi:[1,0]
	v_pk_mul_f32 v[58:59], v[58:59], v[54:55] op_sel_hi:[1,0]
	v_pk_mul_f32 v[62:63], v[52:53], v[54:55] op_sel_hi:[1,0]
	v_pk_mul_f32 v[52:53], v[50:51], v[54:55] op_sel_hi:[1,0]
	v_cvt_pk_bf16_f32 v50, v58, v59
	v_cvt_pk_bf16_f32 v51, v60, v61
	v_pk_mul_f32 v[48:49], v[48:49], v[54:55] op_sel_hi:[1,0]
	v_cvt_pk_bf16_f32 v52, v52, v53
	v_cvt_pk_bf16_f32 v53, v62, v63
	s_cmp_lg_u64 s[4:5], 0
	s_cbranch_scc1 .Lwt_40
	global_store_dwordx4 v[56:57], v[50:53], off
.Lwb_40:
	v_pk_mul_f32 v[46:47], v[46:47], v[54:55] op_sel_hi:[1,0]
	s_nop 0
	v_pk_mul_f32 v[50:51], v[40:41], v[54:55] op_sel_hi:[1,0]
	v_pk_mul_f32 v[40:41], v[38:39], v[54:55] op_sel_hi:[1,0]
	v_cvt_pk_bf16_f32 v38, v46, v47
	v_cvt_pk_bf16_f32 v39, v48, v49
	s_nop 0
	v_cvt_pk_bf16_f32 v40, v40, v41
	v_cvt_pk_bf16_f32 v41, v50, v51
	s_cmp_lg_u64 s[4:5], 0
	s_cbranch_scc1 .Lwt_41
	global_store_dwordx4 v[56:57], v[38:41], off offset:256
.Lwb_41:
	ds_read_b32 v38, v142 offset:384
	s_nop 0
	v_add_u32_e32 v39, 0xa0, v164
	v_mad_i64_i32 v[40:41], s[2:3], v39, s10, v[76:77]
	v_lshl_add_u64 v[40:41], v[40:41], 0, v[140:141]
	s_waitcnt lgkmcnt(0)
	v_pk_mul_f32 v[44:45], v[44:45], v[38:39] op_sel_hi:[1,0]
	v_pk_mul_f32 v[42:43], v[42:43], v[38:39] op_sel_hi:[1,0]
	v_pk_mul_f32 v[46:47], v[36:37], v[38:39] op_sel_hi:[1,0]
	v_pk_mul_f32 v[36:37], v[34:35], v[38:39] op_sel_hi:[1,0]
	v_cvt_pk_bf16_f32 v34, v42, v43
	v_cvt_pk_bf16_f32 v35, v44, v45
	v_pk_mul_f32 v[32:33], v[32:33], v[38:39] op_sel_hi:[1,0]
	v_cvt_pk_bf16_f32 v36, v36, v37
	v_cvt_pk_bf16_f32 v37, v46, v47
	s_cmp_lg_u64 s[4:5], 0
	s_cbranch_scc1 .Lwt_42
	global_store_dwordx4 v[40:41], v[34:37], off
.Lwb_42:
	v_pk_mul_f32 v[30:31], v[30:31], v[38:39] op_sel_hi:[1,0]
	s_nop 0
	v_pk_mul_f32 v[34:35], v[28:29], v[38:39] op_sel_hi:[1,0]
	v_pk_mul_f32 v[28:29], v[26:27], v[38:39] op_sel_hi:[1,0]
	v_cvt_pk_bf16_f32 v26, v30, v31
	v_cvt_pk_bf16_f32 v27, v32, v33
	s_nop 0
	v_cvt_pk_bf16_f32 v28, v28, v29
	v_cvt_pk_bf16_f32 v29, v34, v35
	s_cmp_lg_u64 s[4:5], 0
	s_cbranch_scc1 .Lwt_43
	global_store_dwordx4 v[40:41], v[26:29], off offset:256
.Lwb_43:
	ds_read_b32 v28, v142 offset:448
	s_nop 0
	v_add_u32_e32 v29, 0xb0, v164
	v_mad_i64_i32 v[26:27], s[2:3], v29, s10, v[76:77]
	v_ashrrev_i32_e32 v29, 6, v29
	v_lshl_add_u32 v30, v29, 1, v29
	v_ashrrev_i32_e32 v31, 31, v30
	v_lshl_add_u64 v[30:31], v[30:31], 0, v[2:3]
	v_readlane_b32 s2, v254, 1
	v_lshlrev_b64 v[30:31], 13, v[30:31]
	s_waitcnt lgkmcnt(0)
	v_pk_mul_f32 v[22:23], v[22:23], v[28:29] op_sel_hi:[1,0]
	v_readlane_b32 s3, v254, 2
	v_pk_mul_f32 v[32:33], v[20:21], v[28:29] op_sel_hi:[1,0]
	v_pk_mul_f32 v[20:21], v[18:19], v[28:29] op_sel_hi:[1,0]
	v_cvt_pk_bf16_f32 v18, v22, v23
	v_lshl_add_u64 v[22:23], s[2:3], 0, v[30:31]
	v_lshl_add_u64 v[26:27], v[26:27], 0, v[140:141]
	v_lshl_add_u64 v[22:23], v[138:139], 1, v[22:23]
	v_pk_mul_f32 v[24:25], v[24:25], v[28:29] op_sel_hi:[1,0]
	s_nop 0
	v_cvt_pk_bf16_f32 v19, v24, v25
	v_cvt_pk_bf16_f32 v20, v20, v21
	v_cvt_pk_bf16_f32 v21, v32, v33
	s_cmp_lg_u64 s[4:5], 0
	s_cbranch_scc1 .Lwt_44
	global_store_dwordx4 v[26:27], v[18:21], off
.Lwb_44:
	s_and_saveexec_b64 s[82:83], s[0:1]
	s_cbranch_execz .LBB0_346
	s_cmp_lg_u64 s[4:5], 0
	s_cbranch_scc1 .Lwt_45
	global_store_dwordx4 v[22:23], v[18:21], off offset:-4096
.Lwb_45:
.LBB0_346:
	s_or_b64 exec, exec, s[82:83]
	v_mov_b32_e32 v29, v28
	v_mov_b32_e32 v18, v28
	v_mov_b32_e32 v19, v28
	v_pk_mul_f32 v[16:17], v[16:17], v[18:19]
	v_pk_mul_f32 v[18:19], v[12:13], v[18:19]
	v_pk_mul_f32 v[12:13], v[10:11], v[28:29]
	v_pk_mul_f32 v[14:15], v[14:15], v[28:29]
	s_nop 0
	v_cvt_pk_bf16_f32 v10, v14, v15
	v_cvt_pk_bf16_f32 v11, v16, v17
	v_cvt_pk_bf16_f32 v12, v12, v13
	v_cvt_pk_bf16_f32 v13, v18, v19
	s_cmp_lg_u64 s[4:5], 0
	s_cbranch_scc1 .Lwt_46
	global_store_dwordx4 v[26:27], v[10:13], off offset:256
.Lwb_46:
	s_and_saveexec_b64 s[82:83], s[0:1]
	s_cbranch_execz .LBB0_348
	s_cmp_lg_u64 s[4:5], 0
	s_cbranch_scc1 .Lwt_47
	global_store_dwordx4 v[22:23], v[10:13], off offset:-3840
.Lwb_47:
.LBB0_348:
	s_or_b64 exec, exec, s[82:83]
	s_and_b64 vcc, exec, s[4:5]
	s_mov_b64 s[0:1], -1
	s_cbranch_vccnz .LBB0_320

; __device__ __forceinline__ unsigned pk2(float lo, float hi) { unsigned r; asm volatile("v_cvt_pk_bf16_f32 %0, %1, %2" : "=v"(r) : "v"(lo), "v"(hi)); return r; }
;     __device__ __forceinline__ void fast(const f32x4 (&acc)[2][2][4][2], const pg8::Unit& u, int wr, int wc, int fr, int fq, RsCache& rsc) const {
;     ...
;             for (int ai = 0; ai < 2; ++ai)
; #pragma unroll
;                 for (int m = 0; m < 4; ++m) { const int row = row0 + ai * 128 + m * 16; const float s = rsc.tab[ai * 64 + m * 16 + fr]; bf16_t* rowp = big + (size_t)row * BIGW + cb;
; #pragma unroll
;                     for (int bj = 0; bj < 2; ++bj) { const f32x4 v0 = acc[ai][bj][m][0] * s, v1 = acc[ai][bj][m][1] * s;
;                         u32x4 w; w.x = pk2(v0[0], v0[1]); w.y = pk2(v0[2], v0[3]); w.z = pk2(v1[0], v1[1]); w.w = pk2(v1[2], v1[3]);
;                         *(u32x4*)(rowp + bj * 128) = w;
;                         if (m == 3 && hal) *(u32x4*)(halo + ((size_t)(row >> 6) * 3 + (fr - 13)) * 4096 + (cb - DI_) + bj * 128) = w; }
;                     asm volatile("" ::: "memory"); }
.Lwt_28:
	global_store_dwordx4 v[148:149], v[130:133], off sc1
	s_branch .Lwb_28
.Lwt_29:
	global_store_dwordx4 v[148:149], v[118:121], off offset:256 sc1
	s_branch .Lwb_29
.Lwt_30:
	global_store_dwordx4 v[120:121], v[114:117], off sc1
	s_branch .Lwb_30
.Lwt_31:
	global_store_dwordx4 v[120:121], v[102:105], off offset:256 sc1
	s_branch .Lwb_31
.Lwt_32:
	global_store_dwordx4 v[104:105], v[98:101], off sc1
	s_branch .Lwb_32
.Lwt_33:
	global_store_dwordx4 v[104:105], v[90:93], off offset:256 sc1
	s_branch .Lwb_33
.Lwt_34:
	global_store_dwordx4 v[90:91], v[82:85], off sc1
	s_branch .Lwb_34
.Lwt_35:
	global_store_dwordx4 v[86:87], v[82:85], off offset:-4096 sc1
	s_branch .Lwb_35
.Lwt_36:
	global_store_dwordx4 v[90:91], v[74:77], off offset:256 sc1
	s_branch .Lwb_36
.Lwt_37:
	global_store_dwordx4 v[86:87], v[74:77], off offset:-3840 sc1
	s_branch .Lwb_37
.Lwt_38:
	global_store_dwordx4 v[78:79], v[66:69], off sc1
	s_branch .Lwb_38
.Lwt_39:
	global_store_dwordx4 v[78:79], v[54:57], off offset:256 sc1
	s_branch .Lwb_39
.Lwt_40:
	global_store_dwordx4 v[56:57], v[50:53], off sc1
	s_branch .Lwb_40
.Lwt_41:
	global_store_dwordx4 v[56:57], v[38:41], off offset:256 sc1
	s_branch .Lwb_41
.Lwt_42:
	global_store_dwordx4 v[40:41], v[34:37], off sc1
	s_branch .Lwb_42
.Lwt_43:
	global_store_dwordx4 v[40:41], v[26:29], off offset:256 sc1
	s_branch .Lwb_43
.Lwt_44:
	global_store_dwordx4 v[26:27], v[18:21], off sc1
	s_branch .Lwb_44
.Lwt_45:
	global_store_dwordx4 v[22:23], v[18:21], off offset:-4096 sc1
	s_branch .Lwb_45
.Lwt_46:
	global_store_dwordx4 v[26:27], v[10:13], off offset:256 sc1
	s_branch .Lwb_46
.Lwt_47:
	global_store_dwordx4 v[22:23], v[10:13], off offset:-3840 sc1
	s_branch .Lwb_47
